# phase_norm latent rows: hand-written path with modulation params held in registers and double-buffered row loads (was 8 serialized parameter round trips per row)
# speedup vs baseline: 1.0358x; 1.0079x over previous
; __device__ __forceinline__ void phase_norm(KP p, int l, int which, int nrows) {
;     ...
;   const float* mods = (const float*)(p->ws + OFF_MODS) + (size_t)l * 3 * 12288;
;   const float* g = p->in[which ? 7 : 6] + (size_t)l * DM;
;   u16* A = (u16*)(p->ws + OFF_A);
;   const int lane = tid_ & 63, wv = tid_ >> 6;
;   const int sh = which ? 3 : 0, scl = which ? 4 : 1;
;   const int stride = gridDim.x * 8;
;   float4 va[8], vb[8];
;     ...
;   int r = bid_ * 8 + wv;
;   if (r < nrows) NORM_LOAD(va, r);
.LBB0_132:
	v_writelane_b32 v255, s38, 8
	s_xor_b64 s[6:7], s[38:39], -1
	s_nop 0
	v_writelane_b32 v255, s39, 9
	v_writelane_b32 v255, s6, 10
	s_nop 1
	v_writelane_b32 v255, s7, 11
	v_readlane_b32 s6, v254, 59
	v_readlane_b32 s7, v254, 60
	s_mov_b32 s19, s7
	v_writelane_b32 v255, s18, 12
	s_mul_i32 s6, s18, 0x24000
	s_nop 0
	v_writelane_b32 v255, s19, 13
	v_writelane_b32 v255, s6, 14
	v_readlane_b32 s6, v254, 40
	s_cmp_lt_i32 s6, s68
	s_cselect_b64 s[42:43], -1, 0
	s_cmp_ge_i32 s6, s69
	s_cselect_b64 s[6:7], -1, 0
	s_or_b64 s[6:7], s[6:7], s[42:43]
	s_and_b64 vcc, exec, s[6:7]
	s_cbranch_vccnz .LBB0_171
	s_load_dwordx2 s[14:15], s[0:1], 0xe0
	s_load_dwordx2 s[40:41], s[0:1], 0xd8
	s_load_dwordx2 s[48:49], s[0:1], 0x30
	v_readlane_b32 s18, v255, 12
	s_load_dwordx2 s[50:51], s[0:1], 0x0
	s_waitcnt lgkmcnt(0)
	s_cmp_eq_u32 s18, 0
	s_cselect_b32 s40, s50, s40
	s_cselect_b32 s41, s51, s41
	s_lshl_b32 s19, s18, 13
	s_add_u32 s48, s48, s19
	s_addc_u32 s49, s49, 0
	s_mul_i32 s19, s18, 0x24000
	s_add_u32 s50, s14, s19
	s_addc_u32 s51, s15, 0
	s_add_u32 s46, s14, 0xaa00000
	s_addc_u32 s47, s15, 0
	s_add_u32 s52, s50, 0x0
	s_addc_u32 s53, s51, 0
	s_add_u32 s50, s50, 0x2000
	s_addc_u32 s51, s51, 0
	v_and_b32_e32 v128, 63, v135
	v_lshlrev_b32_e32 v129, 4, v128
	v_lshrrev_b32_e32 v131, 6, v135
	s_lshl_b32 s19, s78, 3
	v_add_u32_e32 v131, s19, v131
	v_lshl_add_u32 v136, v131, 13, v129
	v_add_u32_e32 v137, 0x1000, v136
	v_lshrrev_b32_e32 v132, 1, v136
	global_load_dwordx4 v[96:99], v136, s[40:41]
	global_load_dwordx4 v[100:103], v136, s[40:41] offset:1024
	global_load_dwordx4 v[104:107], v136, s[40:41] offset:2048
	global_load_dwordx4 v[108:111], v136, s[40:41] offset:3072
	global_load_dwordx4 v[112:115], v137, s[40:41]
	global_load_dwordx4 v[116:119], v137, s[40:41] offset:1024
	global_load_dwordx4 v[120:123], v137, s[40:41] offset:2048
	global_load_dwordx4 v[124:127], v137, s[40:41] offset:3072
	s_mov_b32 s7, 0
.Lnorm0_block:
	v_and_b32_e32 v128, 63, v135
	v_lshlrev_b32_e32 v129, 4, v128
	v_add_u32_e32 v130, 0x1000, v129
	global_load_dwordx4 v[0:3], v129, s[48:49]
	global_load_dwordx4 v[4:7], v129, s[48:49] offset:1024
	global_load_dwordx4 v[8:11], v129, s[48:49] offset:2048
	global_load_dwordx4 v[12:15], v129, s[48:49] offset:3072
	global_load_dwordx4 v[16:19], v130, s[48:49]
	global_load_dwordx4 v[20:23], v130, s[48:49] offset:1024
	global_load_dwordx4 v[24:27], v130, s[48:49] offset:2048
	global_load_dwordx4 v[28:31], v130, s[48:49] offset:3072
	global_load_dwordx4 v[32:35], v129, s[50:51]
	global_load_dwordx4 v[36:39], v129, s[50:51] offset:1024
	global_load_dwordx4 v[40:43], v129, s[50:51] offset:2048
	global_load_dwordx4 v[44:47], v129, s[50:51] offset:3072
	global_load_dwordx4 v[48:51], v130, s[50:51]
	global_load_dwordx4 v[52:55], v130, s[50:51] offset:1024
	global_load_dwordx4 v[56:59], v130, s[50:51] offset:2048
	global_load_dwordx4 v[60:63], v130, s[50:51] offset:3072
	global_load_dwordx4 v[64:67], v129, s[52:53]
	global_load_dwordx4 v[68:71], v129, s[52:53] offset:1024
	global_load_dwordx4 v[72:75], v129, s[52:53] offset:2048
	global_load_dwordx4 v[76:79], v129, s[52:53] offset:3072
	global_load_dwordx4 v[80:83], v130, s[52:53]
	global_load_dwordx4 v[84:87], v130, s[52:53] offset:1024
	global_load_dwordx4 v[88:91], v130, s[52:53] offset:2048
	global_load_dwordx4 v[92:95], v130, s[52:53] offset:3072
	s_waitcnt vmcnt(0)
	v_pk_add_f32 v[32:33], v[32:33], 1.0 op_sel_hi:[1,0]
	v_pk_add_f32 v[34:35], v[34:35], 1.0 op_sel_hi:[1,0]
	v_pk_add_f32 v[36:37], v[36:37], 1.0 op_sel_hi:[1,0]
	v_pk_add_f32 v[38:39], v[38:39], 1.0 op_sel_hi:[1,0]
	v_pk_add_f32 v[40:41], v[40:41], 1.0 op_sel_hi:[1,0]
	v_pk_add_f32 v[42:43], v[42:43], 1.0 op_sel_hi:[1,0]
	v_pk_add_f32 v[44:45], v[44:45], 1.0 op_sel_hi:[1,0]
	v_pk_add_f32 v[46:47], v[46:47], 1.0 op_sel_hi:[1,0]
	v_pk_add_f32 v[48:49], v[48:49], 1.0 op_sel_hi:[1,0]
	v_pk_add_f32 v[50:51], v[50:51], 1.0 op_sel_hi:[1,0]
	v_pk_add_f32 v[52:53], v[52:53], 1.0 op_sel_hi:[1,0]
	v_pk_add_f32 v[54:55], v[54:55], 1.0 op_sel_hi:[1,0]
	v_pk_add_f32 v[56:57], v[56:57], 1.0 op_sel_hi:[1,0]
	v_pk_add_f32 v[58:59], v[58:59], 1.0 op_sel_hi:[1,0]
	v_pk_add_f32 v[60:61], v[60:61], 1.0 op_sel_hi:[1,0]
	v_pk_add_f32 v[62:63], v[62:63], 1.0 op_sel_hi:[1,0]
	v_add_u32_e32 v136, 0x1000000, v136
	v_add_u32_e32 v137, 0x1000000, v137
	global_load_dwordx4 v[140:143], v136, s[40:41]
	global_load_dwordx4 v[144:147], v136, s[40:41] offset:1024
	global_load_dwordx4 v[148:151], v136, s[40:41] offset:2048
	global_load_dwordx4 v[152:155], v136, s[40:41] offset:3072
	global_load_dwordx4 v[156:159], v137, s[40:41]
	global_load_dwordx4 v[160:163], v137, s[40:41] offset:1024
	global_load_dwordx4 v[164:167], v137, s[40:41] offset:2048
	global_load_dwordx4 v[168:171], v137, s[40:41] offset:3072
	v_pk_mul_f32 v[128:129], v[96:97], v[96:97]
	v_pk_fma_f32 v[128:129], v[98:99], v[98:99], v[128:129]
	v_pk_fma_f32 v[128:129], v[100:101], v[100:101], v[128:129]
	v_pk_fma_f32 v[128:129], v[102:103], v[102:103], v[128:129]
	v_pk_fma_f32 v[128:129], v[104:105], v[104:105], v[128:129]
	v_pk_fma_f32 v[128:129], v[106:107], v[106:107], v[128:129]
	v_pk_fma_f32 v[128:129], v[108:109], v[108:109], v[128:129]
	v_pk_fma_f32 v[128:129], v[110:111], v[110:111], v[128:129]
	v_pk_fma_f32 v[128:129], v[112:113], v[112:113], v[128:129]
	v_pk_fma_f32 v[128:129], v[114:115], v[114:115], v[128:129]
	v_pk_fma_f32 v[128:129], v[116:117], v[116:117], v[128:129]
	v_pk_fma_f32 v[128:129], v[118:119], v[118:119], v[128:129]
	v_pk_fma_f32 v[128:129], v[120:121], v[120:121], v[128:129]
	v_pk_fma_f32 v[128:129], v[122:123], v[122:123], v[128:129]
	v_pk_fma_f32 v[128:129], v[124:125], v[124:125], v[128:129]
; __device__ __forceinline__ void phase_norm(KP p, int l, int which, int nrows) {
;     ...
;   int r = bid_ * 8 + wv;
;   if (r < nrows) NORM_LOAD(va, r);
;   for (; r < nrows; r += 2 * stride) {
;     if (r + stride < nrows) NORM_LOAD(vb, r + stride);
;     NORM_BODY(va, r);
;     if (r + 2 * stride < nrows) NORM_LOAD(va, r + 2 * stride);
	v_pk_fma_f32 v[128:129], v[126:127], v[126:127], v[128:129]
	v_add_f32_e32 v130, v128, v129
	s_nop 1
	v_add_f32_dpp v130, v130, v130 quad_perm:[1,0,3,2] row_mask:0xf bank_mask:0xf bound_ctrl:1
	s_nop 1
	v_add_f32_dpp v130, v130, v130 quad_perm:[2,3,0,1] row_mask:0xf bank_mask:0xf bound_ctrl:1
	s_nop 1
	v_add_f32_dpp v130, v130, v130 row_half_mirror row_mask:0xf bank_mask:0xf bound_ctrl:1
	s_nop 1
	v_add_f32_dpp v130, v130, v130 row_mirror row_mask:0xf bank_mask:0xf bound_ctrl:1
	s_nop 0
	v_readlane_b32 s14, v130, 0
	v_readlane_b32 s15, v130, 16
	v_readlane_b32 s6, v130, 32
	v_readlane_b32 s19, v130, 48
	s_nop 0
	v_mov_b32_e32 v128, s15
	v_add_f32_e32 v128, s14, v128
	v_mov_b32_e32 v129, s19
	v_add_f32_e32 v129, s6, v129
	v_add_f32_e32 v128, v128, v129
	v_mov_b32_e32 v129, 0x358637bd
	v_fmamk_f32 v128, v128, 0x3a000000, v129
	v_rsq_f32_e32 v128, v128
	s_nop 0
	v_readfirstlane_b32 s54, v128
	s_nop 1
	v_pk_mul_f32 v[128:129], v[96:97], s[54:55] op_sel_hi:[1,0]
	v_pk_mul_f32 v[130:131], v[98:99], s[54:55] op_sel_hi:[1,0]
	v_pk_mul_f32 v[128:129], v[0:1], v[128:129]
	v_pk_mul_f32 v[130:131], v[2:3], v[130:131]
	v_pk_fma_f32 v[128:129], v[32:33], v[128:129], v[64:65]
	v_pk_fma_f32 v[130:131], v[34:35], v[130:131], v[66:67]
	v_cvt_pk_bf16_f32 v128, v128, v129
	v_cvt_pk_bf16_f32 v129, v130, v131
	global_store_dwordx2 v132, v[128:129], s[46:47]
	v_pk_mul_f32 v[128:129], v[100:101], s[54:55] op_sel_hi:[1,0]
	v_pk_mul_f32 v[130:131], v[102:103], s[54:55] op_sel_hi:[1,0]
	v_pk_mul_f32 v[128:129], v[4:5], v[128:129]
	v_pk_mul_f32 v[130:131], v[6:7], v[130:131]
	v_pk_fma_f32 v[128:129], v[36:37], v[128:129], v[68:69]
	v_pk_fma_f32 v[130:131], v[38:39], v[130:131], v[70:71]
	v_cvt_pk_bf16_f32 v128, v128, v129
	v_cvt_pk_bf16_f32 v129, v130, v131
	global_store_dwordx2 v132, v[128:129], s[46:47] offset:512
	v_pk_mul_f32 v[128:129], v[104:105], s[54:55] op_sel_hi:[1,0]
	v_pk_mul_f32 v[130:131], v[106:107], s[54:55] op_sel_hi:[1,0]
	v_pk_mul_f32 v[128:129], v[8:9], v[128:129]
	v_pk_mul_f32 v[130:131], v[10:11], v[130:131]
	v_pk_fma_f32 v[128:129], v[40:41], v[128:129], v[72:73]
	v_pk_fma_f32 v[130:131], v[42:43], v[130:131], v[74:75]
	v_cvt_pk_bf16_f32 v128, v128, v129
	v_cvt_pk_bf16_f32 v129, v130, v131
	global_store_dwordx2 v132, v[128:129], s[46:47] offset:1024
	v_pk_mul_f32 v[128:129], v[108:109], s[54:55] op_sel_hi:[1,0]
	v_pk_mul_f32 v[130:131], v[110:111], s[54:55] op_sel_hi:[1,0]
	v_pk_mul_f32 v[128:129], v[12:13], v[128:129]
	v_pk_mul_f32 v[130:131], v[14:15], v[130:131]
	v_pk_fma_f32 v[128:129], v[44:45], v[128:129], v[76:77]
	v_pk_fma_f32 v[130:131], v[46:47], v[130:131], v[78:79]
	v_cvt_pk_bf16_f32 v128, v128, v129
	v_cvt_pk_bf16_f32 v129, v130, v131
	global_store_dwordx2 v132, v[128:129], s[46:47] offset:1536
	v_pk_mul_f32 v[128:129], v[112:113], s[54:55] op_sel_hi:[1,0]
	v_pk_mul_f32 v[130:131], v[114:115], s[54:55] op_sel_hi:[1,0]
	v_pk_mul_f32 v[128:129], v[16:17], v[128:129]
	v_pk_mul_f32 v[130:131], v[18:19], v[130:131]
	v_pk_fma_f32 v[128:129], v[48:49], v[128:129], v[80:81]
	v_pk_fma_f32 v[130:131], v[50:51], v[130:131], v[82:83]
	v_cvt_pk_bf16_f32 v128, v128, v129
	v_cvt_pk_bf16_f32 v129, v130, v131
	global_store_dwordx2 v132, v[128:129], s[46:47] offset:2048
	v_pk_mul_f32 v[128:129], v[116:117], s[54:55] op_sel_hi:[1,0]
	v_pk_mul_f32 v[130:131], v[118:119], s[54:55] op_sel_hi:[1,0]
	v_pk_mul_f32 v[128:129], v[20:21], v[128:129]
	v_pk_mul_f32 v[130:131], v[22:23], v[130:131]
	v_pk_fma_f32 v[128:129], v[52:53], v[128:129], v[84:85]
	v_pk_fma_f32 v[130:131], v[54:55], v[130:131], v[86:87]
	v_cvt_pk_bf16_f32 v128, v128, v129
	v_cvt_pk_bf16_f32 v129, v130, v131
	global_store_dwordx2 v132, v[128:129], s[46:47] offset:2560
	v_pk_mul_f32 v[128:129], v[120:121], s[54:55] op_sel_hi:[1,0]
	v_pk_mul_f32 v[130:131], v[122:123], s[54:55] op_sel_hi:[1,0]
	v_pk_mul_f32 v[128:129], v[24:25], v[128:129]
	v_pk_mul_f32 v[130:131], v[26:27], v[130:131]
	v_pk_fma_f32 v[128:129], v[56:57], v[128:129], v[88:89]
	v_pk_fma_f32 v[130:131], v[58:59], v[130:131], v[90:91]
	v_cvt_pk_bf16_f32 v128, v128, v129
	v_cvt_pk_bf16_f32 v129, v130, v131
	global_store_dwordx2 v132, v[128:129], s[46:47] offset:3072
	v_pk_mul_f32 v[128:129], v[124:125], s[54:55] op_sel_hi:[1,0]
	v_pk_mul_f32 v[130:131], v[126:127], s[54:55] op_sel_hi:[1,0]
	v_pk_mul_f32 v[128:129], v[28:29], v[128:129]
	v_pk_mul_f32 v[130:131], v[30:31], v[130:131]
	v_pk_fma_f32 v[128:129], v[60:61], v[128:129], v[92:93]
	v_pk_fma_f32 v[130:131], v[62:63], v[130:131], v[94:95]
	v_cvt_pk_bf16_f32 v128, v128, v129
	v_cvt_pk_bf16_f32 v129, v130, v131
	global_store_dwordx2 v132, v[128:129], s[46:47] offset:3584
	v_add_u32_e32 v132, 0x800000, v132
	v_add_u32_e32 v136, 0x1000000, v136
	v_add_u32_e32 v137, 0x1000000, v137
	global_load_dwordx4 v[96:99], v136, s[40:41]
	global_load_dwordx4 v[100:103], v136, s[40:41] offset:1024
	global_load_dwordx4 v[104:107], v136, s[40:41] offset:2048
	global_load_dwordx4 v[108:111], v136, s[40:41] offset:3072
	global_load_dwordx4 v[112:115], v137, s[40:41]
	global_load_dwordx4 v[116:119], v137, s[40:41] offset:1024
	global_load_dwordx4 v[120:123], v137, s[40:41] offset:2048
	global_load_dwordx4 v[124:127], v137, s[40:41] offset:3072
	s_waitcnt vmcnt(16)
; __device__ __forceinline__ void phase_norm(KP p, int l, int which, int nrows) {
;     ...
;   int r = bid_ * 8 + wv;
;   if (r < nrows) NORM_LOAD(va, r);
;   for (; r < nrows; r += 2 * stride) {
;     if (r + stride < nrows) NORM_LOAD(vb, r + stride);
;     NORM_BODY(va, r);
;     if (r + 2 * stride < nrows) NORM_LOAD(va, r + 2 * stride);
	v_pk_mul_f32 v[128:129], v[140:141], v[140:141]
	v_pk_fma_f32 v[128:129], v[142:143], v[142:143], v[128:129]
	v_pk_fma_f32 v[128:129], v[144:145], v[144:145], v[128:129]
	v_pk_fma_f32 v[128:129], v[146:147], v[146:147], v[128:129]
	v_pk_fma_f32 v[128:129], v[148:149], v[148:149], v[128:129]
	v_pk_fma_f32 v[128:129], v[150:151], v[150:151], v[128:129]
	v_pk_fma_f32 v[128:129], v[152:153], v[152:153], v[128:129]
	v_pk_fma_f32 v[128:129], v[154:155], v[154:155], v[128:129]
	v_pk_fma_f32 v[128:129], v[156:157], v[156:157], v[128:129]
	v_pk_fma_f32 v[128:129], v[158:159], v[158:159], v[128:129]
	v_pk_fma_f32 v[128:129], v[160:161], v[160:161], v[128:129]
	v_pk_fma_f32 v[128:129], v[162:163], v[162:163], v[128:129]
	v_pk_fma_f32 v[128:129], v[164:165], v[164:165], v[128:129]
	v_pk_fma_f32 v[128:129], v[166:167], v[166:167], v[128:129]
	v_pk_fma_f32 v[128:129], v[168:169], v[168:169], v[128:129]
	v_pk_fma_f32 v[128:129], v[170:171], v[170:171], v[128:129]
	v_add_f32_e32 v130, v128, v129
	s_nop 1
	v_add_f32_dpp v130, v130, v130 quad_perm:[1,0,3,2] row_mask:0xf bank_mask:0xf bound_ctrl:1
	s_nop 1
	v_add_f32_dpp v130, v130, v130 quad_perm:[2,3,0,1] row_mask:0xf bank_mask:0xf bound_ctrl:1
	s_nop 1
	v_add_f32_dpp v130, v130, v130 row_half_mirror row_mask:0xf bank_mask:0xf bound_ctrl:1
	s_nop 1
	v_add_f32_dpp v130, v130, v130 row_mirror row_mask:0xf bank_mask:0xf bound_ctrl:1
	s_nop 0
	v_readlane_b32 s14, v130, 0
	v_readlane_b32 s15, v130, 16
	v_readlane_b32 s6, v130, 32
	v_readlane_b32 s19, v130, 48
	s_nop 0
	v_mov_b32_e32 v128, s15
	v_add_f32_e32 v128, s14, v128
	v_mov_b32_e32 v129, s19
	v_add_f32_e32 v129, s6, v129
	v_add_f32_e32 v128, v128, v129
	v_mov_b32_e32 v129, 0x358637bd
	v_fmamk_f32 v128, v128, 0x3a000000, v129
	v_rsq_f32_e32 v128, v128
	s_nop 0
	v_readfirstlane_b32 s54, v128
	s_nop 1
	v_pk_mul_f32 v[128:129], v[140:141], s[54:55] op_sel_hi:[1,0]
	v_pk_mul_f32 v[130:131], v[142:143], s[54:55] op_sel_hi:[1,0]
	v_pk_mul_f32 v[128:129], v[0:1], v[128:129]
	v_pk_mul_f32 v[130:131], v[2:3], v[130:131]
	v_pk_fma_f32 v[128:129], v[32:33], v[128:129], v[64:65]
	v_pk_fma_f32 v[130:131], v[34:35], v[130:131], v[66:67]
	v_cvt_pk_bf16_f32 v128, v128, v129
	v_cvt_pk_bf16_f32 v129, v130, v131
	global_store_dwordx2 v132, v[128:129], s[46:47]
	v_pk_mul_f32 v[128:129], v[144:145], s[54:55] op_sel_hi:[1,0]
	v_pk_mul_f32 v[130:131], v[146:147], s[54:55] op_sel_hi:[1,0]
	v_pk_mul_f32 v[128:129], v[4:5], v[128:129]
	v_pk_mul_f32 v[130:131], v[6:7], v[130:131]
	v_pk_fma_f32 v[128:129], v[36:37], v[128:129], v[68:69]
	v_pk_fma_f32 v[130:131], v[38:39], v[130:131], v[70:71]
	v_cvt_pk_bf16_f32 v128, v128, v129
	v_cvt_pk_bf16_f32 v129, v130, v131
	global_store_dwordx2 v132, v[128:129], s[46:47] offset:512
	v_pk_mul_f32 v[128:129], v[148:149], s[54:55] op_sel_hi:[1,0]
	v_pk_mul_f32 v[130:131], v[150:151], s[54:55] op_sel_hi:[1,0]
	v_pk_mul_f32 v[128:129], v[8:9], v[128:129]
	v_pk_mul_f32 v[130:131], v[10:11], v[130:131]
	v_pk_fma_f32 v[128:129], v[40:41], v[128:129], v[72:73]
	v_pk_fma_f32 v[130:131], v[42:43], v[130:131], v[74:75]
	v_cvt_pk_bf16_f32 v128, v128, v129
	v_cvt_pk_bf16_f32 v129, v130, v131
	global_store_dwordx2 v132, v[128:129], s[46:47] offset:1024
	v_pk_mul_f32 v[128:129], v[152:153], s[54:55] op_sel_hi:[1,0]
	v_pk_mul_f32 v[130:131], v[154:155], s[54:55] op_sel_hi:[1,0]
	v_pk_mul_f32 v[128:129], v[12:13], v[128:129]
	v_pk_mul_f32 v[130:131], v[14:15], v[130:131]
	v_pk_fma_f32 v[128:129], v[44:45], v[128:129], v[76:77]
	v_pk_fma_f32 v[130:131], v[46:47], v[130:131], v[78:79]
	v_cvt_pk_bf16_f32 v128, v128, v129
	v_cvt_pk_bf16_f32 v129, v130, v131
	global_store_dwordx2 v132, v[128:129], s[46:47] offset:1536
	v_pk_mul_f32 v[128:129], v[156:157], s[54:55] op_sel_hi:[1,0]
	v_pk_mul_f32 v[130:131], v[158:159], s[54:55] op_sel_hi:[1,0]
	v_pk_mul_f32 v[128:129], v[16:17], v[128:129]
	v_pk_mul_f32 v[130:131], v[18:19], v[130:131]
	v_pk_fma_f32 v[128:129], v[48:49], v[128:129], v[80:81]
	v_pk_fma_f32 v[130:131], v[50:51], v[130:131], v[82:83]
	v_cvt_pk_bf16_f32 v128, v128, v129
	v_cvt_pk_bf16_f32 v129, v130, v131
	global_store_dwordx2 v132, v[128:129], s[46:47] offset:2048
	v_pk_mul_f32 v[128:129], v[160:161], s[54:55] op_sel_hi:[1,0]
	v_pk_mul_f32 v[130:131], v[162:163], s[54:55] op_sel_hi:[1,0]
	v_pk_mul_f32 v[128:129], v[20:21], v[128:129]
	v_pk_mul_f32 v[130:131], v[22:23], v[130:131]
	v_pk_fma_f32 v[128:129], v[52:53], v[128:129], v[84:85]
	v_pk_fma_f32 v[130:131], v[54:55], v[130:131], v[86:87]
	v_cvt_pk_bf16_f32 v128, v128, v129
	v_cvt_pk_bf16_f32 v129, v130, v131
	global_store_dwordx2 v132, v[128:129], s[46:47] offset:2560
	v_pk_mul_f32 v[128:129], v[164:165], s[54:55] op_sel_hi:[1,0]
	v_pk_mul_f32 v[130:131], v[166:167], s[54:55] op_sel_hi:[1,0]
	v_pk_mul_f32 v[128:129], v[24:25], v[128:129]
	v_pk_mul_f32 v[130:131], v[26:27], v[130:131]
	v_pk_fma_f32 v[128:129], v[56:57], v[128:129], v[88:89]
	v_pk_fma_f32 v[130:131], v[58:59], v[130:131], v[90:91]
	v_cvt_pk_bf16_f32 v128, v128, v129
	v_cvt_pk_bf16_f32 v129, v130, v131
	global_store_dwordx2 v132, v[128:129], s[46:47] offset:3072
	v_pk_mul_f32 v[128:129], v[168:169], s[54:55] op_sel_hi:[1,0]
	v_pk_mul_f32 v[130:131], v[170:171], s[54:55] op_sel_hi:[1,0]
	v_pk_mul_f32 v[128:129], v[28:29], v[128:129]
	v_pk_mul_f32 v[130:131], v[30:31], v[130:131]
	v_pk_fma_f32 v[128:129], v[60:61], v[128:129], v[92:93]
	v_pk_fma_f32 v[130:131], v[62:63], v[130:131], v[94:95]
	v_cvt_pk_bf16_f32 v128, v128, v129
	v_cvt_pk_bf16_f32 v129, v130, v131
	global_store_dwordx2 v132, v[128:129], s[46:47] offset:3584
	v_add_u32_e32 v132, 0x800000, v132
	v_add_u32_e32 v136, 0x1000000, v136
	v_add_u32_e32 v137, 0x1000000, v137
	global_load_dwordx4 v[140:143], v136, s[40:41]
	global_load_dwordx4 v[144:147], v136, s[40:41] offset:1024
	global_load_dwordx4 v[148:151], v136, s[40:41] offset:2048
	global_load_dwordx4 v[152:155], v136, s[40:41] offset:3072
	global_load_dwordx4 v[156:159], v137, s[40:41]
	global_load_dwordx4 v[160:163], v137, s[40:41] offset:1024
	global_load_dwordx4 v[164:167], v137, s[40:41] offset:2048
	global_load_dwordx4 v[168:171], v137, s[40:41] offset:3072
	s_waitcnt vmcnt(16)
; __device__ __forceinline__ void phase_norm(KP p, int l, int which, int nrows) {
;     ...
;   int r = bid_ * 8 + wv;
;   if (r < nrows) NORM_LOAD(va, r);
;   for (; r < nrows; r += 2 * stride) {
;     if (r + stride < nrows) NORM_LOAD(vb, r + stride);
;     NORM_BODY(va, r);
;     if (r + 2 * stride < nrows) NORM_LOAD(va, r + 2 * stride);
	v_pk_mul_f32 v[128:129], v[96:97], v[96:97]
	v_pk_fma_f32 v[128:129], v[98:99], v[98:99], v[128:129]
	v_pk_fma_f32 v[128:129], v[100:101], v[100:101], v[128:129]
	v_pk_fma_f32 v[128:129], v[102:103], v[102:103], v[128:129]
	v_pk_fma_f32 v[128:129], v[104:105], v[104:105], v[128:129]
	v_pk_fma_f32 v[128:129], v[106:107], v[106:107], v[128:129]
	v_pk_fma_f32 v[128:129], v[108:109], v[108:109], v[128:129]
	v_pk_fma_f32 v[128:129], v[110:111], v[110:111], v[128:129]
	v_pk_fma_f32 v[128:129], v[112:113], v[112:113], v[128:129]
	v_pk_fma_f32 v[128:129], v[114:115], v[114:115], v[128:129]
	v_pk_fma_f32 v[128:129], v[116:117], v[116:117], v[128:129]
	v_pk_fma_f32 v[128:129], v[118:119], v[118:119], v[128:129]
	v_pk_fma_f32 v[128:129], v[120:121], v[120:121], v[128:129]
	v_pk_fma_f32 v[128:129], v[122:123], v[122:123], v[128:129]
	v_pk_fma_f32 v[128:129], v[124:125], v[124:125], v[128:129]
	v_pk_fma_f32 v[128:129], v[126:127], v[126:127], v[128:129]
	v_add_f32_e32 v130, v128, v129
	s_nop 1
	v_add_f32_dpp v130, v130, v130 quad_perm:[1,0,3,2] row_mask:0xf bank_mask:0xf bound_ctrl:1
	s_nop 1
	v_add_f32_dpp v130, v130, v130 quad_perm:[2,3,0,1] row_mask:0xf bank_mask:0xf bound_ctrl:1
	s_nop 1
	v_add_f32_dpp v130, v130, v130 row_half_mirror row_mask:0xf bank_mask:0xf bound_ctrl:1
	s_nop 1
	v_add_f32_dpp v130, v130, v130 row_mirror row_mask:0xf bank_mask:0xf bound_ctrl:1
	s_nop 0
	v_readlane_b32 s14, v130, 0
	v_readlane_b32 s15, v130, 16
	v_readlane_b32 s6, v130, 32
	v_readlane_b32 s19, v130, 48
	s_nop 0
	v_mov_b32_e32 v128, s15
	v_add_f32_e32 v128, s14, v128
	v_mov_b32_e32 v129, s19
	v_add_f32_e32 v129, s6, v129
	v_add_f32_e32 v128, v128, v129
	v_mov_b32_e32 v129, 0x358637bd
	v_fmamk_f32 v128, v128, 0x3a000000, v129
	v_rsq_f32_e32 v128, v128
	s_nop 0
	v_readfirstlane_b32 s54, v128
	s_nop 1
	v_pk_mul_f32 v[128:129], v[96:97], s[54:55] op_sel_hi:[1,0]
	v_pk_mul_f32 v[130:131], v[98:99], s[54:55] op_sel_hi:[1,0]
	v_pk_mul_f32 v[128:129], v[0:1], v[128:129]
	v_pk_mul_f32 v[130:131], v[2:3], v[130:131]
	v_pk_fma_f32 v[128:129], v[32:33], v[128:129], v[64:65]
	v_pk_fma_f32 v[130:131], v[34:35], v[130:131], v[66:67]
	v_cvt_pk_bf16_f32 v128, v128, v129
	v_cvt_pk_bf16_f32 v129, v130, v131
	global_store_dwordx2 v132, v[128:129], s[46:47]
	v_pk_mul_f32 v[128:129], v[100:101], s[54:55] op_sel_hi:[1,0]
	v_pk_mul_f32 v[130:131], v[102:103], s[54:55] op_sel_hi:[1,0]
	v_pk_mul_f32 v[128:129], v[4:5], v[128:129]
	v_pk_mul_f32 v[130:131], v[6:7], v[130:131]
	v_pk_fma_f32 v[128:129], v[36:37], v[128:129], v[68:69]
	v_pk_fma_f32 v[130:131], v[38:39], v[130:131], v[70:71]
	v_cvt_pk_bf16_f32 v128, v128, v129
	v_cvt_pk_bf16_f32 v129, v130, v131
	global_store_dwordx2 v132, v[128:129], s[46:47] offset:512
	v_pk_mul_f32 v[128:129], v[104:105], s[54:55] op_sel_hi:[1,0]
	v_pk_mul_f32 v[130:131], v[106:107], s[54:55] op_sel_hi:[1,0]
	v_pk_mul_f32 v[128:129], v[8:9], v[128:129]
	v_pk_mul_f32 v[130:131], v[10:11], v[130:131]
	v_pk_fma_f32 v[128:129], v[40:41], v[128:129], v[72:73]
	v_pk_fma_f32 v[130:131], v[42:43], v[130:131], v[74:75]
	v_cvt_pk_bf16_f32 v128, v128, v129
	v_cvt_pk_bf16_f32 v129, v130, v131
	global_store_dwordx2 v132, v[128:129], s[46:47] offset:1024
	v_pk_mul_f32 v[128:129], v[108:109], s[54:55] op_sel_hi:[1,0]
	v_pk_mul_f32 v[130:131], v[110:111], s[54:55] op_sel_hi:[1,0]
	v_pk_mul_f32 v[128:129], v[12:13], v[128:129]
	v_pk_mul_f32 v[130:131], v[14:15], v[130:131]
	v_pk_fma_f32 v[128:129], v[44:45], v[128:129], v[76:77]
	v_pk_fma_f32 v[130:131], v[46:47], v[130:131], v[78:79]
	v_cvt_pk_bf16_f32 v128, v128, v129
	v_cvt_pk_bf16_f32 v129, v130, v131
	global_store_dwordx2 v132, v[128:129], s[46:47] offset:1536
	v_pk_mul_f32 v[128:129], v[112:113], s[54:55] op_sel_hi:[1,0]
	v_pk_mul_f32 v[130:131], v[114:115], s[54:55] op_sel_hi:[1,0]
	v_pk_mul_f32 v[128:129], v[16:17], v[128:129]
	v_pk_mul_f32 v[130:131], v[18:19], v[130:131]
	v_pk_fma_f32 v[128:129], v[48:49], v[128:129], v[80:81]
	v_pk_fma_f32 v[130:131], v[50:51], v[130:131], v[82:83]
	v_cvt_pk_bf16_f32 v128, v128, v129
	v_cvt_pk_bf16_f32 v129, v130, v131
	global_store_dwordx2 v132, v[128:129], s[46:47] offset:2048
	v_pk_mul_f32 v[128:129], v[116:117], s[54:55] op_sel_hi:[1,0]
	v_pk_mul_f32 v[130:131], v[118:119], s[54:55] op_sel_hi:[1,0]
	v_pk_mul_f32 v[128:129], v[20:21], v[128:129]
	v_pk_mul_f32 v[130:131], v[22:23], v[130:131]
	v_pk_fma_f32 v[128:129], v[52:53], v[128:129], v[84:85]
	v_pk_fma_f32 v[130:131], v[54:55], v[130:131], v[86:87]
	v_cvt_pk_bf16_f32 v128, v128, v129
	v_cvt_pk_bf16_f32 v129, v130, v131
	global_store_dwordx2 v132, v[128:129], s[46:47] offset:2560
	v_pk_mul_f32 v[128:129], v[120:121], s[54:55] op_sel_hi:[1,0]
	v_pk_mul_f32 v[130:131], v[122:123], s[54:55] op_sel_hi:[1,0]
	v_pk_mul_f32 v[128:129], v[24:25], v[128:129]
	v_pk_mul_f32 v[130:131], v[26:27], v[130:131]
	v_pk_fma_f32 v[128:129], v[56:57], v[128:129], v[88:89]
	v_pk_fma_f32 v[130:131], v[58:59], v[130:131], v[90:91]
	v_cvt_pk_bf16_f32 v128, v128, v129
	v_cvt_pk_bf16_f32 v129, v130, v131
	global_store_dwordx2 v132, v[128:129], s[46:47] offset:3072
	v_pk_mul_f32 v[128:129], v[124:125], s[54:55] op_sel_hi:[1,0]
	v_pk_mul_f32 v[130:131], v[126:127], s[54:55] op_sel_hi:[1,0]
	v_pk_mul_f32 v[128:129], v[28:29], v[128:129]
	v_pk_mul_f32 v[130:131], v[30:31], v[130:131]
	v_pk_fma_f32 v[128:129], v[60:61], v[128:129], v[92:93]
	v_pk_fma_f32 v[130:131], v[62:63], v[130:131], v[94:95]
	v_cvt_pk_bf16_f32 v128, v128, v129
	v_cvt_pk_bf16_f32 v129, v130, v131
	global_store_dwordx2 v132, v[128:129], s[46:47] offset:3584
	v_add_u32_e32 v132, 0x800000, v132
	v_add_u32_e32 v136, 0x1000000, v136
	v_add_u32_e32 v137, 0x1000000, v137
	global_load_dwordx4 v[96:99], v136, s[40:41]
	global_load_dwordx4 v[100:103], v136, s[40:41] offset:1024
	global_load_dwordx4 v[104:107], v136, s[40:41] offset:2048
	global_load_dwordx4 v[108:111], v136, s[40:41] offset:3072
	global_load_dwordx4 v[112:115], v137, s[40:41]
	global_load_dwordx4 v[116:119], v137, s[40:41] offset:1024
	global_load_dwordx4 v[120:123], v137, s[40:41] offset:2048
	global_load_dwordx4 v[124:127], v137, s[40:41] offset:3072
	s_waitcnt vmcnt(16)
; __device__ __forceinline__ void phase_norm(KP p, int l, int which, int nrows) {
;     ...
;   int r = bid_ * 8 + wv;
;   if (r < nrows) NORM_LOAD(va, r);
;   for (; r < nrows; r += 2 * stride) {
;     if (r + stride < nrows) NORM_LOAD(vb, r + stride);
;     NORM_BODY(va, r);
;     if (r + 2 * stride < nrows) NORM_LOAD(va, r + 2 * stride);
	v_pk_mul_f32 v[128:129], v[140:141], v[140:141]
	v_pk_fma_f32 v[128:129], v[142:143], v[142:143], v[128:129]
	v_pk_fma_f32 v[128:129], v[144:145], v[144:145], v[128:129]
	v_pk_fma_f32 v[128:129], v[146:147], v[146:147], v[128:129]
	v_pk_fma_f32 v[128:129], v[148:149], v[148:149], v[128:129]
	v_pk_fma_f32 v[128:129], v[150:151], v[150:151], v[128:129]
	v_pk_fma_f32 v[128:129], v[152:153], v[152:153], v[128:129]
	v_pk_fma_f32 v[128:129], v[154:155], v[154:155], v[128:129]
	v_pk_fma_f32 v[128:129], v[156:157], v[156:157], v[128:129]
	v_pk_fma_f32 v[128:129], v[158:159], v[158:159], v[128:129]
	v_pk_fma_f32 v[128:129], v[160:161], v[160:161], v[128:129]
	v_pk_fma_f32 v[128:129], v[162:163], v[162:163], v[128:129]
	v_pk_fma_f32 v[128:129], v[164:165], v[164:165], v[128:129]
	v_pk_fma_f32 v[128:129], v[166:167], v[166:167], v[128:129]
	v_pk_fma_f32 v[128:129], v[168:169], v[168:169], v[128:129]
	v_pk_fma_f32 v[128:129], v[170:171], v[170:171], v[128:129]
	v_add_f32_e32 v130, v128, v129
	s_nop 1
	v_add_f32_dpp v130, v130, v130 quad_perm:[1,0,3,2] row_mask:0xf bank_mask:0xf bound_ctrl:1
	s_nop 1
	v_add_f32_dpp v130, v130, v130 quad_perm:[2,3,0,1] row_mask:0xf bank_mask:0xf bound_ctrl:1
	s_nop 1
	v_add_f32_dpp v130, v130, v130 row_half_mirror row_mask:0xf bank_mask:0xf bound_ctrl:1
	s_nop 1
	v_add_f32_dpp v130, v130, v130 row_mirror row_mask:0xf bank_mask:0xf bound_ctrl:1
	s_nop 0
	v_readlane_b32 s14, v130, 0
	v_readlane_b32 s15, v130, 16
	v_readlane_b32 s6, v130, 32
	v_readlane_b32 s19, v130, 48
	s_nop 0
	v_mov_b32_e32 v128, s15
	v_add_f32_e32 v128, s14, v128
	v_mov_b32_e32 v129, s19
	v_add_f32_e32 v129, s6, v129
	v_add_f32_e32 v128, v128, v129
	v_mov_b32_e32 v129, 0x358637bd
	v_fmamk_f32 v128, v128, 0x3a000000, v129
	v_rsq_f32_e32 v128, v128
	s_nop 0
	v_readfirstlane_b32 s54, v128
	s_nop 1
	v_pk_mul_f32 v[128:129], v[140:141], s[54:55] op_sel_hi:[1,0]
	v_pk_mul_f32 v[130:131], v[142:143], s[54:55] op_sel_hi:[1,0]
	v_pk_mul_f32 v[128:129], v[0:1], v[128:129]
	v_pk_mul_f32 v[130:131], v[2:3], v[130:131]
	v_pk_fma_f32 v[128:129], v[32:33], v[128:129], v[64:65]
	v_pk_fma_f32 v[130:131], v[34:35], v[130:131], v[66:67]
	v_cvt_pk_bf16_f32 v128, v128, v129
	v_cvt_pk_bf16_f32 v129, v130, v131
	global_store_dwordx2 v132, v[128:129], s[46:47]
	v_pk_mul_f32 v[128:129], v[144:145], s[54:55] op_sel_hi:[1,0]
	v_pk_mul_f32 v[130:131], v[146:147], s[54:55] op_sel_hi:[1,0]
	v_pk_mul_f32 v[128:129], v[4:5], v[128:129]
	v_pk_mul_f32 v[130:131], v[6:7], v[130:131]
	v_pk_fma_f32 v[128:129], v[36:37], v[128:129], v[68:69]
	v_pk_fma_f32 v[130:131], v[38:39], v[130:131], v[70:71]
	v_cvt_pk_bf16_f32 v128, v128, v129
	v_cvt_pk_bf16_f32 v129, v130, v131
	global_store_dwordx2 v132, v[128:129], s[46:47] offset:512
	v_pk_mul_f32 v[128:129], v[148:149], s[54:55] op_sel_hi:[1,0]
	v_pk_mul_f32 v[130:131], v[150:151], s[54:55] op_sel_hi:[1,0]
	v_pk_mul_f32 v[128:129], v[8:9], v[128:129]
	v_pk_mul_f32 v[130:131], v[10:11], v[130:131]
	v_pk_fma_f32 v[128:129], v[40:41], v[128:129], v[72:73]
	v_pk_fma_f32 v[130:131], v[42:43], v[130:131], v[74:75]
	v_cvt_pk_bf16_f32 v128, v128, v129
	v_cvt_pk_bf16_f32 v129, v130, v131
	global_store_dwordx2 v132, v[128:129], s[46:47] offset:1024
	v_pk_mul_f32 v[128:129], v[152:153], s[54:55] op_sel_hi:[1,0]
	v_pk_mul_f32 v[130:131], v[154:155], s[54:55] op_sel_hi:[1,0]
	v_pk_mul_f32 v[128:129], v[12:13], v[128:129]
	v_pk_mul_f32 v[130:131], v[14:15], v[130:131]
	v_pk_fma_f32 v[128:129], v[44:45], v[128:129], v[76:77]
	v_pk_fma_f32 v[130:131], v[46:47], v[130:131], v[78:79]
	v_cvt_pk_bf16_f32 v128, v128, v129
	v_cvt_pk_bf16_f32 v129, v130, v131
	global_store_dwordx2 v132, v[128:129], s[46:47] offset:1536
	v_pk_mul_f32 v[128:129], v[156:157], s[54:55] op_sel_hi:[1,0]
	v_pk_mul_f32 v[130:131], v[158:159], s[54:55] op_sel_hi:[1,0]
	v_pk_mul_f32 v[128:129], v[16:17], v[128:129]
	v_pk_mul_f32 v[130:131], v[18:19], v[130:131]
	v_pk_fma_f32 v[128:129], v[48:49], v[128:129], v[80:81]
	v_pk_fma_f32 v[130:131], v[50:51], v[130:131], v[82:83]
	v_cvt_pk_bf16_f32 v128, v128, v129
	v_cvt_pk_bf16_f32 v129, v130, v131
	global_store_dwordx2 v132, v[128:129], s[46:47] offset:2048
	v_pk_mul_f32 v[128:129], v[160:161], s[54:55] op_sel_hi:[1,0]
	v_pk_mul_f32 v[130:131], v[162:163], s[54:55] op_sel_hi:[1,0]
	v_pk_mul_f32 v[128:129], v[20:21], v[128:129]
	v_pk_mul_f32 v[130:131], v[22:23], v[130:131]
	v_pk_fma_f32 v[128:129], v[52:53], v[128:129], v[84:85]
	v_pk_fma_f32 v[130:131], v[54:55], v[130:131], v[86:87]
	v_cvt_pk_bf16_f32 v128, v128, v129
	v_cvt_pk_bf16_f32 v129, v130, v131
	global_store_dwordx2 v132, v[128:129], s[46:47] offset:2560
	v_pk_mul_f32 v[128:129], v[164:165], s[54:55] op_sel_hi:[1,0]
	v_pk_mul_f32 v[130:131], v[166:167], s[54:55] op_sel_hi:[1,0]
	v_pk_mul_f32 v[128:129], v[24:25], v[128:129]
	v_pk_mul_f32 v[130:131], v[26:27], v[130:131]
	v_pk_fma_f32 v[128:129], v[56:57], v[128:129], v[88:89]
	v_pk_fma_f32 v[130:131], v[58:59], v[130:131], v[90:91]
	v_cvt_pk_bf16_f32 v128, v128, v129
	v_cvt_pk_bf16_f32 v129, v130, v131
	global_store_dwordx2 v132, v[128:129], s[46:47] offset:3072
	v_pk_mul_f32 v[128:129], v[168:169], s[54:55] op_sel_hi:[1,0]
	v_pk_mul_f32 v[130:131], v[170:171], s[54:55] op_sel_hi:[1,0]
	v_pk_mul_f32 v[128:129], v[28:29], v[128:129]
	v_pk_mul_f32 v[130:131], v[30:31], v[130:131]
	v_pk_fma_f32 v[128:129], v[60:61], v[128:129], v[92:93]
	v_pk_fma_f32 v[130:131], v[62:63], v[130:131], v[94:95]
	v_cvt_pk_bf16_f32 v128, v128, v129
	v_cvt_pk_bf16_f32 v129, v130, v131
	global_store_dwordx2 v132, v[128:129], s[46:47] offset:3584
	v_add_u32_e32 v132, 0x800000, v132
	v_add_u32_e32 v136, 0x1000000, v136
	v_add_u32_e32 v137, 0x1000000, v137
	global_load_dwordx4 v[140:143], v136, s[40:41]
	global_load_dwordx4 v[144:147], v136, s[40:41] offset:1024
	global_load_dwordx4 v[148:151], v136, s[40:41] offset:2048
	global_load_dwordx4 v[152:155], v136, s[40:41] offset:3072
	global_load_dwordx4 v[156:159], v137, s[40:41]
	global_load_dwordx4 v[160:163], v137, s[40:41] offset:1024
	global_load_dwordx4 v[164:167], v137, s[40:41] offset:2048
	global_load_dwordx4 v[168:171], v137, s[40:41] offset:3072
	s_waitcnt vmcnt(16)
; __device__ __forceinline__ void phase_norm(KP p, int l, int which, int nrows) {
;     ...
;   int r = bid_ * 8 + wv;
;   if (r < nrows) NORM_LOAD(va, r);
;   for (; r < nrows; r += 2 * stride) {
;     if (r + stride < nrows) NORM_LOAD(vb, r + stride);
;     NORM_BODY(va, r);
;     if (r + 2 * stride < nrows) NORM_LOAD(va, r + 2 * stride);
	v_pk_mul_f32 v[128:129], v[96:97], v[96:97]
	v_pk_fma_f32 v[128:129], v[98:99], v[98:99], v[128:129]
	v_pk_fma_f32 v[128:129], v[100:101], v[100:101], v[128:129]
	v_pk_fma_f32 v[128:129], v[102:103], v[102:103], v[128:129]
	v_pk_fma_f32 v[128:129], v[104:105], v[104:105], v[128:129]
	v_pk_fma_f32 v[128:129], v[106:107], v[106:107], v[128:129]
	v_pk_fma_f32 v[128:129], v[108:109], v[108:109], v[128:129]
	v_pk_fma_f32 v[128:129], v[110:111], v[110:111], v[128:129]
	v_pk_fma_f32 v[128:129], v[112:113], v[112:113], v[128:129]
	v_pk_fma_f32 v[128:129], v[114:115], v[114:115], v[128:129]
	v_pk_fma_f32 v[128:129], v[116:117], v[116:117], v[128:129]
	v_pk_fma_f32 v[128:129], v[118:119], v[118:119], v[128:129]
	v_pk_fma_f32 v[128:129], v[120:121], v[120:121], v[128:129]
	v_pk_fma_f32 v[128:129], v[122:123], v[122:123], v[128:129]
	v_pk_fma_f32 v[128:129], v[124:125], v[124:125], v[128:129]
	v_pk_fma_f32 v[128:129], v[126:127], v[126:127], v[128:129]
	v_add_f32_e32 v130, v128, v129
	s_nop 1
	v_add_f32_dpp v130, v130, v130 quad_perm:[1,0,3,2] row_mask:0xf bank_mask:0xf bound_ctrl:1
	s_nop 1
	v_add_f32_dpp v130, v130, v130 quad_perm:[2,3,0,1] row_mask:0xf bank_mask:0xf bound_ctrl:1
	s_nop 1
	v_add_f32_dpp v130, v130, v130 row_half_mirror row_mask:0xf bank_mask:0xf bound_ctrl:1
	s_nop 1
	v_add_f32_dpp v130, v130, v130 row_mirror row_mask:0xf bank_mask:0xf bound_ctrl:1
	s_nop 0
	v_readlane_b32 s14, v130, 0
	v_readlane_b32 s15, v130, 16
	v_readlane_b32 s6, v130, 32
	v_readlane_b32 s19, v130, 48
	s_nop 0
	v_mov_b32_e32 v128, s15
	v_add_f32_e32 v128, s14, v128
	v_mov_b32_e32 v129, s19
	v_add_f32_e32 v129, s6, v129
	v_add_f32_e32 v128, v128, v129
	v_mov_b32_e32 v129, 0x358637bd
	v_fmamk_f32 v128, v128, 0x3a000000, v129
	v_rsq_f32_e32 v128, v128
	s_nop 0
	v_readfirstlane_b32 s54, v128
	s_nop 1
	v_pk_mul_f32 v[128:129], v[96:97], s[54:55] op_sel_hi:[1,0]
	v_pk_mul_f32 v[130:131], v[98:99], s[54:55] op_sel_hi:[1,0]
	v_pk_mul_f32 v[128:129], v[0:1], v[128:129]
	v_pk_mul_f32 v[130:131], v[2:3], v[130:131]
	v_pk_fma_f32 v[128:129], v[32:33], v[128:129], v[64:65]
	v_pk_fma_f32 v[130:131], v[34:35], v[130:131], v[66:67]
	v_cvt_pk_bf16_f32 v128, v128, v129
	v_cvt_pk_bf16_f32 v129, v130, v131
	global_store_dwordx2 v132, v[128:129], s[46:47]
	v_pk_mul_f32 v[128:129], v[100:101], s[54:55] op_sel_hi:[1,0]
	v_pk_mul_f32 v[130:131], v[102:103], s[54:55] op_sel_hi:[1,0]
	v_pk_mul_f32 v[128:129], v[4:5], v[128:129]
	v_pk_mul_f32 v[130:131], v[6:7], v[130:131]
	v_pk_fma_f32 v[128:129], v[36:37], v[128:129], v[68:69]
	v_pk_fma_f32 v[130:131], v[38:39], v[130:131], v[70:71]
	v_cvt_pk_bf16_f32 v128, v128, v129
	v_cvt_pk_bf16_f32 v129, v130, v131
	global_store_dwordx2 v132, v[128:129], s[46:47] offset:512
	v_pk_mul_f32 v[128:129], v[104:105], s[54:55] op_sel_hi:[1,0]
	v_pk_mul_f32 v[130:131], v[106:107], s[54:55] op_sel_hi:[1,0]
	v_pk_mul_f32 v[128:129], v[8:9], v[128:129]
	v_pk_mul_f32 v[130:131], v[10:11], v[130:131]
	v_pk_fma_f32 v[128:129], v[40:41], v[128:129], v[72:73]
	v_pk_fma_f32 v[130:131], v[42:43], v[130:131], v[74:75]
	v_cvt_pk_bf16_f32 v128, v128, v129
	v_cvt_pk_bf16_f32 v129, v130, v131
	global_store_dwordx2 v132, v[128:129], s[46:47] offset:1024
	v_pk_mul_f32 v[128:129], v[108:109], s[54:55] op_sel_hi:[1,0]
	v_pk_mul_f32 v[130:131], v[110:111], s[54:55] op_sel_hi:[1,0]
	v_pk_mul_f32 v[128:129], v[12:13], v[128:129]
	v_pk_mul_f32 v[130:131], v[14:15], v[130:131]
	v_pk_fma_f32 v[128:129], v[44:45], v[128:129], v[76:77]
	v_pk_fma_f32 v[130:131], v[46:47], v[130:131], v[78:79]
	v_cvt_pk_bf16_f32 v128, v128, v129
	v_cvt_pk_bf16_f32 v129, v130, v131
	global_store_dwordx2 v132, v[128:129], s[46:47] offset:1536
	v_pk_mul_f32 v[128:129], v[112:113], s[54:55] op_sel_hi:[1,0]
	v_pk_mul_f32 v[130:131], v[114:115], s[54:55] op_sel_hi:[1,0]
	v_pk_mul_f32 v[128:129], v[16:17], v[128:129]
	v_pk_mul_f32 v[130:131], v[18:19], v[130:131]
	v_pk_fma_f32 v[128:129], v[48:49], v[128:129], v[80:81]
	v_pk_fma_f32 v[130:131], v[50:51], v[130:131], v[82:83]
	v_cvt_pk_bf16_f32 v128, v128, v129
	v_cvt_pk_bf16_f32 v129, v130, v131
	global_store_dwordx2 v132, v[128:129], s[46:47] offset:2048
	v_pk_mul_f32 v[128:129], v[116:117], s[54:55] op_sel_hi:[1,0]
	v_pk_mul_f32 v[130:131], v[118:119], s[54:55] op_sel_hi:[1,0]
	v_pk_mul_f32 v[128:129], v[20:21], v[128:129]
	v_pk_mul_f32 v[130:131], v[22:23], v[130:131]
	v_pk_fma_f32 v[128:129], v[52:53], v[128:129], v[84:85]
	v_pk_fma_f32 v[130:131], v[54:55], v[130:131], v[86:87]
	v_cvt_pk_bf16_f32 v128, v128, v129
	v_cvt_pk_bf16_f32 v129, v130, v131
	global_store_dwordx2 v132, v[128:129], s[46:47] offset:2560
	v_pk_mul_f32 v[128:129], v[120:121], s[54:55] op_sel_hi:[1,0]
	v_pk_mul_f32 v[130:131], v[122:123], s[54:55] op_sel_hi:[1,0]
	v_pk_mul_f32 v[128:129], v[24:25], v[128:129]
	v_pk_mul_f32 v[130:131], v[26:27], v[130:131]
	v_pk_fma_f32 v[128:129], v[56:57], v[128:129], v[88:89]
	v_pk_fma_f32 v[130:131], v[58:59], v[130:131], v[90:91]
	v_cvt_pk_bf16_f32 v128, v128, v129
	v_cvt_pk_bf16_f32 v129, v130, v131
	global_store_dwordx2 v132, v[128:129], s[46:47] offset:3072
	v_pk_mul_f32 v[128:129], v[124:125], s[54:55] op_sel_hi:[1,0]
	v_pk_mul_f32 v[130:131], v[126:127], s[54:55] op_sel_hi:[1,0]
	v_pk_mul_f32 v[128:129], v[28:29], v[128:129]
	v_pk_mul_f32 v[130:131], v[30:31], v[130:131]
	v_pk_fma_f32 v[128:129], v[60:61], v[128:129], v[92:93]
	v_pk_fma_f32 v[130:131], v[62:63], v[130:131], v[94:95]
	v_cvt_pk_bf16_f32 v128, v128, v129
	v_cvt_pk_bf16_f32 v129, v130, v131
	global_store_dwordx2 v132, v[128:129], s[46:47] offset:3584
	v_add_u32_e32 v132, 0x800000, v132
	v_add_u32_e32 v136, 0x1000000, v136
	v_add_u32_e32 v137, 0x1000000, v137
	global_load_dwordx4 v[96:99], v136, s[40:41]
	global_load_dwordx4 v[100:103], v136, s[40:41] offset:1024
	global_load_dwordx4 v[104:107], v136, s[40:41] offset:2048
	global_load_dwordx4 v[108:111], v136, s[40:41] offset:3072
	global_load_dwordx4 v[112:115], v137, s[40:41]
	global_load_dwordx4 v[116:119], v137, s[40:41] offset:1024
	global_load_dwordx4 v[120:123], v137, s[40:41] offset:2048
	global_load_dwordx4 v[124:127], v137, s[40:41] offset:3072
	s_waitcnt vmcnt(16)
; __device__ __forceinline__ void phase_norm(KP p, int l, int which, int nrows) {
;     ...
;   int r = bid_ * 8 + wv;
;   if (r < nrows) NORM_LOAD(va, r);
;   for (; r < nrows; r += 2 * stride) {
;     if (r + stride < nrows) NORM_LOAD(vb, r + stride);
;     NORM_BODY(va, r);
;     if (r + 2 * stride < nrows) NORM_LOAD(va, r + 2 * stride);
;     if (r + stride < nrows) NORM_BODY(vb, r + stride);
;   }
	v_pk_mul_f32 v[128:129], v[140:141], v[140:141]
	v_pk_fma_f32 v[128:129], v[142:143], v[142:143], v[128:129]
	v_pk_fma_f32 v[128:129], v[144:145], v[144:145], v[128:129]
	v_pk_fma_f32 v[128:129], v[146:147], v[146:147], v[128:129]
	v_pk_fma_f32 v[128:129], v[148:149], v[148:149], v[128:129]
	v_pk_fma_f32 v[128:129], v[150:151], v[150:151], v[128:129]
	v_pk_fma_f32 v[128:129], v[152:153], v[152:153], v[128:129]
	v_pk_fma_f32 v[128:129], v[154:155], v[154:155], v[128:129]
	v_pk_fma_f32 v[128:129], v[156:157], v[156:157], v[128:129]
	v_pk_fma_f32 v[128:129], v[158:159], v[158:159], v[128:129]
	v_pk_fma_f32 v[128:129], v[160:161], v[160:161], v[128:129]
	v_pk_fma_f32 v[128:129], v[162:163], v[162:163], v[128:129]
	v_pk_fma_f32 v[128:129], v[164:165], v[164:165], v[128:129]
	v_pk_fma_f32 v[128:129], v[166:167], v[166:167], v[128:129]
	v_pk_fma_f32 v[128:129], v[168:169], v[168:169], v[128:129]
	v_pk_fma_f32 v[128:129], v[170:171], v[170:171], v[128:129]
	v_add_f32_e32 v130, v128, v129
	s_nop 1
	v_add_f32_dpp v130, v130, v130 quad_perm:[1,0,3,2] row_mask:0xf bank_mask:0xf bound_ctrl:1
	s_nop 1
	v_add_f32_dpp v130, v130, v130 quad_perm:[2,3,0,1] row_mask:0xf bank_mask:0xf bound_ctrl:1
	s_nop 1
	v_add_f32_dpp v130, v130, v130 row_half_mirror row_mask:0xf bank_mask:0xf bound_ctrl:1
	s_nop 1
	v_add_f32_dpp v130, v130, v130 row_mirror row_mask:0xf bank_mask:0xf bound_ctrl:1
	s_nop 0
	v_readlane_b32 s14, v130, 0
	v_readlane_b32 s15, v130, 16
	v_readlane_b32 s6, v130, 32
	v_readlane_b32 s19, v130, 48
	s_nop 0
	v_mov_b32_e32 v128, s15
	v_add_f32_e32 v128, s14, v128
	v_mov_b32_e32 v129, s19
	v_add_f32_e32 v129, s6, v129
	v_add_f32_e32 v128, v128, v129
	v_mov_b32_e32 v129, 0x358637bd
	v_fmamk_f32 v128, v128, 0x3a000000, v129
	v_rsq_f32_e32 v128, v128
	s_nop 0
	v_readfirstlane_b32 s54, v128
	s_nop 1
	v_pk_mul_f32 v[128:129], v[140:141], s[54:55] op_sel_hi:[1,0]
	v_pk_mul_f32 v[130:131], v[142:143], s[54:55] op_sel_hi:[1,0]
	v_pk_mul_f32 v[128:129], v[0:1], v[128:129]
	v_pk_mul_f32 v[130:131], v[2:3], v[130:131]
	v_pk_fma_f32 v[128:129], v[32:33], v[128:129], v[64:65]
	v_pk_fma_f32 v[130:131], v[34:35], v[130:131], v[66:67]
	v_cvt_pk_bf16_f32 v128, v128, v129
	v_cvt_pk_bf16_f32 v129, v130, v131
	global_store_dwordx2 v132, v[128:129], s[46:47]
	v_pk_mul_f32 v[128:129], v[144:145], s[54:55] op_sel_hi:[1,0]
	v_pk_mul_f32 v[130:131], v[146:147], s[54:55] op_sel_hi:[1,0]
	v_pk_mul_f32 v[128:129], v[4:5], v[128:129]
	v_pk_mul_f32 v[130:131], v[6:7], v[130:131]
	v_pk_fma_f32 v[128:129], v[36:37], v[128:129], v[68:69]
	v_pk_fma_f32 v[130:131], v[38:39], v[130:131], v[70:71]
	v_cvt_pk_bf16_f32 v128, v128, v129
	v_cvt_pk_bf16_f32 v129, v130, v131
	global_store_dwordx2 v132, v[128:129], s[46:47] offset:512
	v_pk_mul_f32 v[128:129], v[148:149], s[54:55] op_sel_hi:[1,0]
	v_pk_mul_f32 v[130:131], v[150:151], s[54:55] op_sel_hi:[1,0]
	v_pk_mul_f32 v[128:129], v[8:9], v[128:129]
	v_pk_mul_f32 v[130:131], v[10:11], v[130:131]
	v_pk_fma_f32 v[128:129], v[40:41], v[128:129], v[72:73]
	v_pk_fma_f32 v[130:131], v[42:43], v[130:131], v[74:75]
	v_cvt_pk_bf16_f32 v128, v128, v129
	v_cvt_pk_bf16_f32 v129, v130, v131
	global_store_dwordx2 v132, v[128:129], s[46:47] offset:1024
	v_pk_mul_f32 v[128:129], v[152:153], s[54:55] op_sel_hi:[1,0]
	v_pk_mul_f32 v[130:131], v[154:155], s[54:55] op_sel_hi:[1,0]
	v_pk_mul_f32 v[128:129], v[12:13], v[128:129]
	v_pk_mul_f32 v[130:131], v[14:15], v[130:131]
	v_pk_fma_f32 v[128:129], v[44:45], v[128:129], v[76:77]
	v_pk_fma_f32 v[130:131], v[46:47], v[130:131], v[78:79]
	v_cvt_pk_bf16_f32 v128, v128, v129
	v_cvt_pk_bf16_f32 v129, v130, v131
	global_store_dwordx2 v132, v[128:129], s[46:47] offset:1536
	v_pk_mul_f32 v[128:129], v[156:157], s[54:55] op_sel_hi:[1,0]
	v_pk_mul_f32 v[130:131], v[158:159], s[54:55] op_sel_hi:[1,0]
	v_pk_mul_f32 v[128:129], v[16:17], v[128:129]
	v_pk_mul_f32 v[130:131], v[18:19], v[130:131]
	v_pk_fma_f32 v[128:129], v[48:49], v[128:129], v[80:81]
	v_pk_fma_f32 v[130:131], v[50:51], v[130:131], v[82:83]
	v_cvt_pk_bf16_f32 v128, v128, v129
	v_cvt_pk_bf16_f32 v129, v130, v131
	global_store_dwordx2 v132, v[128:129], s[46:47] offset:2048
	v_pk_mul_f32 v[128:129], v[160:161], s[54:55] op_sel_hi:[1,0]
	v_pk_mul_f32 v[130:131], v[162:163], s[54:55] op_sel_hi:[1,0]
	v_pk_mul_f32 v[128:129], v[20:21], v[128:129]
	v_pk_mul_f32 v[130:131], v[22:23], v[130:131]
	v_pk_fma_f32 v[128:129], v[52:53], v[128:129], v[84:85]
	v_pk_fma_f32 v[130:131], v[54:55], v[130:131], v[86:87]
	v_cvt_pk_bf16_f32 v128, v128, v129
	v_cvt_pk_bf16_f32 v129, v130, v131
	global_store_dwordx2 v132, v[128:129], s[46:47] offset:2560
	v_pk_mul_f32 v[128:129], v[164:165], s[54:55] op_sel_hi:[1,0]
	v_pk_mul_f32 v[130:131], v[166:167], s[54:55] op_sel_hi:[1,0]
	v_pk_mul_f32 v[128:129], v[24:25], v[128:129]
	v_pk_mul_f32 v[130:131], v[26:27], v[130:131]
	v_pk_fma_f32 v[128:129], v[56:57], v[128:129], v[88:89]
	v_pk_fma_f32 v[130:131], v[58:59], v[130:131], v[90:91]
	v_cvt_pk_bf16_f32 v128, v128, v129
	v_cvt_pk_bf16_f32 v129, v130, v131
	global_store_dwordx2 v132, v[128:129], s[46:47] offset:3072
	v_pk_mul_f32 v[128:129], v[168:169], s[54:55] op_sel_hi:[1,0]
	v_pk_mul_f32 v[130:131], v[170:171], s[54:55] op_sel_hi:[1,0]
	v_pk_mul_f32 v[128:129], v[28:29], v[128:129]
	v_pk_mul_f32 v[130:131], v[30:31], v[130:131]
	v_pk_fma_f32 v[128:129], v[60:61], v[128:129], v[92:93]
	v_pk_fma_f32 v[130:131], v[62:63], v[130:131], v[94:95]
	v_cvt_pk_bf16_f32 v128, v128, v129
	v_cvt_pk_bf16_f32 v129, v130, v131
	global_store_dwordx2 v132, v[128:129], s[46:47] offset:3584
	v_add_u32_e32 v132, 0x800000, v132
	v_add_u32_e32 v136, 0x1000000, v136
	v_add_u32_e32 v137, 0x1000000, v137
	global_load_dwordx4 v[140:143], v136, s[40:41]
	global_load_dwordx4 v[144:147], v136, s[40:41] offset:1024
	global_load_dwordx4 v[148:151], v136, s[40:41] offset:2048
	global_load_dwordx4 v[152:155], v136, s[40:41] offset:3072
	global_load_dwordx4 v[156:159], v137, s[40:41]
	global_load_dwordx4 v[160:163], v137, s[40:41] offset:1024
	global_load_dwordx4 v[164:167], v137, s[40:41] offset:2048
	global_load_dwordx4 v[168:171], v137, s[40:41] offset:3072
	s_waitcnt vmcnt(16)
; __device__ __forceinline__ void phase_norm(KP p, int l, int which, int nrows) {
;     ...
;   int r = bid_ * 8 + wv;
;   if (r < nrows) NORM_LOAD(va, r);
;   for (; r < nrows; r += 2 * stride) {
;     if (r + stride < nrows) NORM_LOAD(vb, r + stride);
;     NORM_BODY(va, r);
;     if (r + 2 * stride < nrows) NORM_LOAD(va, r + 2 * stride);
;     if (r + stride < nrows) NORM_BODY(vb, r + stride);
;   }
	v_pk_mul_f32 v[128:129], v[96:97], v[96:97]
	v_pk_fma_f32 v[128:129], v[98:99], v[98:99], v[128:129]
	v_pk_fma_f32 v[128:129], v[100:101], v[100:101], v[128:129]
	v_pk_fma_f32 v[128:129], v[102:103], v[102:103], v[128:129]
	v_pk_fma_f32 v[128:129], v[104:105], v[104:105], v[128:129]
	v_pk_fma_f32 v[128:129], v[106:107], v[106:107], v[128:129]
	v_pk_fma_f32 v[128:129], v[108:109], v[108:109], v[128:129]
	v_pk_fma_f32 v[128:129], v[110:111], v[110:111], v[128:129]
	v_pk_fma_f32 v[128:129], v[112:113], v[112:113], v[128:129]
	v_pk_fma_f32 v[128:129], v[114:115], v[114:115], v[128:129]
	v_pk_fma_f32 v[128:129], v[116:117], v[116:117], v[128:129]
	v_pk_fma_f32 v[128:129], v[118:119], v[118:119], v[128:129]
	v_pk_fma_f32 v[128:129], v[120:121], v[120:121], v[128:129]
	v_pk_fma_f32 v[128:129], v[122:123], v[122:123], v[128:129]
	v_pk_fma_f32 v[128:129], v[124:125], v[124:125], v[128:129]
	v_pk_fma_f32 v[128:129], v[126:127], v[126:127], v[128:129]
	v_add_f32_e32 v130, v128, v129
	s_nop 1
	v_add_f32_dpp v130, v130, v130 quad_perm:[1,0,3,2] row_mask:0xf bank_mask:0xf bound_ctrl:1
	s_nop 1
	v_add_f32_dpp v130, v130, v130 quad_perm:[2,3,0,1] row_mask:0xf bank_mask:0xf bound_ctrl:1
	s_nop 1
	v_add_f32_dpp v130, v130, v130 row_half_mirror row_mask:0xf bank_mask:0xf bound_ctrl:1
	s_nop 1
	v_add_f32_dpp v130, v130, v130 row_mirror row_mask:0xf bank_mask:0xf bound_ctrl:1
	s_nop 0
	v_readlane_b32 s14, v130, 0
	v_readlane_b32 s15, v130, 16
	v_readlane_b32 s6, v130, 32
	v_readlane_b32 s19, v130, 48
	s_nop 0
	v_mov_b32_e32 v128, s15
	v_add_f32_e32 v128, s14, v128
	v_mov_b32_e32 v129, s19
	v_add_f32_e32 v129, s6, v129
	v_add_f32_e32 v128, v128, v129
	v_mov_b32_e32 v129, 0x358637bd
	v_fmamk_f32 v128, v128, 0x3a000000, v129
	v_rsq_f32_e32 v128, v128
	s_nop 0
	v_readfirstlane_b32 s54, v128
	s_nop 1
	v_pk_mul_f32 v[128:129], v[96:97], s[54:55] op_sel_hi:[1,0]
	v_pk_mul_f32 v[130:131], v[98:99], s[54:55] op_sel_hi:[1,0]
	v_pk_mul_f32 v[128:129], v[0:1], v[128:129]
	v_pk_mul_f32 v[130:131], v[2:3], v[130:131]
	v_pk_fma_f32 v[128:129], v[32:33], v[128:129], v[64:65]
	v_pk_fma_f32 v[130:131], v[34:35], v[130:131], v[66:67]
	v_cvt_pk_bf16_f32 v128, v128, v129
	v_cvt_pk_bf16_f32 v129, v130, v131
	global_store_dwordx2 v132, v[128:129], s[46:47]
	v_pk_mul_f32 v[128:129], v[100:101], s[54:55] op_sel_hi:[1,0]
	v_pk_mul_f32 v[130:131], v[102:103], s[54:55] op_sel_hi:[1,0]
	v_pk_mul_f32 v[128:129], v[4:5], v[128:129]
	v_pk_mul_f32 v[130:131], v[6:7], v[130:131]
	v_pk_fma_f32 v[128:129], v[36:37], v[128:129], v[68:69]
	v_pk_fma_f32 v[130:131], v[38:39], v[130:131], v[70:71]
	v_cvt_pk_bf16_f32 v128, v128, v129
	v_cvt_pk_bf16_f32 v129, v130, v131
	global_store_dwordx2 v132, v[128:129], s[46:47] offset:512
	v_pk_mul_f32 v[128:129], v[104:105], s[54:55] op_sel_hi:[1,0]
	v_pk_mul_f32 v[130:131], v[106:107], s[54:55] op_sel_hi:[1,0]
	v_pk_mul_f32 v[128:129], v[8:9], v[128:129]
	v_pk_mul_f32 v[130:131], v[10:11], v[130:131]
	v_pk_fma_f32 v[128:129], v[40:41], v[128:129], v[72:73]
	v_pk_fma_f32 v[130:131], v[42:43], v[130:131], v[74:75]
	v_cvt_pk_bf16_f32 v128, v128, v129
	v_cvt_pk_bf16_f32 v129, v130, v131
	global_store_dwordx2 v132, v[128:129], s[46:47] offset:1024
	v_pk_mul_f32 v[128:129], v[108:109], s[54:55] op_sel_hi:[1,0]
	v_pk_mul_f32 v[130:131], v[110:111], s[54:55] op_sel_hi:[1,0]
	v_pk_mul_f32 v[128:129], v[12:13], v[128:129]
	v_pk_mul_f32 v[130:131], v[14:15], v[130:131]
	v_pk_fma_f32 v[128:129], v[44:45], v[128:129], v[76:77]
	v_pk_fma_f32 v[130:131], v[46:47], v[130:131], v[78:79]
	v_cvt_pk_bf16_f32 v128, v128, v129
	v_cvt_pk_bf16_f32 v129, v130, v131
	global_store_dwordx2 v132, v[128:129], s[46:47] offset:1536
	v_pk_mul_f32 v[128:129], v[112:113], s[54:55] op_sel_hi:[1,0]
	v_pk_mul_f32 v[130:131], v[114:115], s[54:55] op_sel_hi:[1,0]
	v_pk_mul_f32 v[128:129], v[16:17], v[128:129]
	v_pk_mul_f32 v[130:131], v[18:19], v[130:131]
	v_pk_fma_f32 v[128:129], v[48:49], v[128:129], v[80:81]
	v_pk_fma_f32 v[130:131], v[50:51], v[130:131], v[82:83]
	v_cvt_pk_bf16_f32 v128, v128, v129
	v_cvt_pk_bf16_f32 v129, v130, v131
	global_store_dwordx2 v132, v[128:129], s[46:47] offset:2048
	v_pk_mul_f32 v[128:129], v[116:117], s[54:55] op_sel_hi:[1,0]
	v_pk_mul_f32 v[130:131], v[118:119], s[54:55] op_sel_hi:[1,0]
	v_pk_mul_f32 v[128:129], v[20:21], v[128:129]
	v_pk_mul_f32 v[130:131], v[22:23], v[130:131]
	v_pk_fma_f32 v[128:129], v[52:53], v[128:129], v[84:85]
	v_pk_fma_f32 v[130:131], v[54:55], v[130:131], v[86:87]
	v_cvt_pk_bf16_f32 v128, v128, v129
	v_cvt_pk_bf16_f32 v129, v130, v131
	global_store_dwordx2 v132, v[128:129], s[46:47] offset:2560
	v_pk_mul_f32 v[128:129], v[120:121], s[54:55] op_sel_hi:[1,0]
	v_pk_mul_f32 v[130:131], v[122:123], s[54:55] op_sel_hi:[1,0]
	v_pk_mul_f32 v[128:129], v[24:25], v[128:129]
	v_pk_mul_f32 v[130:131], v[26:27], v[130:131]
	v_pk_fma_f32 v[128:129], v[56:57], v[128:129], v[88:89]
	v_pk_fma_f32 v[130:131], v[58:59], v[130:131], v[90:91]
	v_cvt_pk_bf16_f32 v128, v128, v129
	v_cvt_pk_bf16_f32 v129, v130, v131
	global_store_dwordx2 v132, v[128:129], s[46:47] offset:3072
	v_pk_mul_f32 v[128:129], v[124:125], s[54:55] op_sel_hi:[1,0]
	v_pk_mul_f32 v[130:131], v[126:127], s[54:55] op_sel_hi:[1,0]
	v_pk_mul_f32 v[128:129], v[28:29], v[128:129]
	v_pk_mul_f32 v[130:131], v[30:31], v[130:131]
	v_pk_fma_f32 v[128:129], v[60:61], v[128:129], v[92:93]
	v_pk_fma_f32 v[130:131], v[62:63], v[130:131], v[94:95]
	v_cvt_pk_bf16_f32 v128, v128, v129
	v_cvt_pk_bf16_f32 v129, v130, v131
	global_store_dwordx2 v132, v[128:129], s[46:47] offset:3584
	v_add_u32_e32 v132, 0x800000, v132
	s_cmp_eq_u32 s7, 1
	s_cbranch_scc1 .Lnorm0_nopf
	v_add_u32_e32 v136, 0x1000000, v136
	v_add_u32_e32 v137, 0x1000000, v137
	global_load_dwordx4 v[96:99], v136, s[40:41]
	global_load_dwordx4 v[100:103], v136, s[40:41] offset:1024
	global_load_dwordx4 v[104:107], v136, s[40:41] offset:2048
	global_load_dwordx4 v[108:111], v136, s[40:41] offset:3072
	global_load_dwordx4 v[112:115], v137, s[40:41]
	global_load_dwordx4 v[116:119], v137, s[40:41] offset:1024
	global_load_dwordx4 v[120:123], v137, s[40:41] offset:2048
	global_load_dwordx4 v[124:127], v137, s[40:41] offset:3072
; __device__ __forceinline__ void phase_norm(KP p, int l, int which, int nrows) {
;     ...
;   int r = bid_ * 8 + wv;
;   if (r < nrows) NORM_LOAD(va, r);
;   for (; r < nrows; r += 2 * stride) {
;     if (r + stride < nrows) NORM_LOAD(vb, r + stride);
;     NORM_BODY(va, r);
;     if (r + 2 * stride < nrows) NORM_LOAD(va, r + 2 * stride);
;     if (r + stride < nrows) NORM_BODY(vb, r + stride);
;   }
.Lnorm0_nopf:
	s_waitcnt vmcnt(8)
	v_pk_mul_f32 v[128:129], v[140:141], v[140:141]
	v_pk_fma_f32 v[128:129], v[142:143], v[142:143], v[128:129]
	v_pk_fma_f32 v[128:129], v[144:145], v[144:145], v[128:129]
	v_pk_fma_f32 v[128:129], v[146:147], v[146:147], v[128:129]
	v_pk_fma_f32 v[128:129], v[148:149], v[148:149], v[128:129]
	v_pk_fma_f32 v[128:129], v[150:151], v[150:151], v[128:129]
	v_pk_fma_f32 v[128:129], v[152:153], v[152:153], v[128:129]
	v_pk_fma_f32 v[128:129], v[154:155], v[154:155], v[128:129]
	v_pk_fma_f32 v[128:129], v[156:157], v[156:157], v[128:129]
	v_pk_fma_f32 v[128:129], v[158:159], v[158:159], v[128:129]
	v_pk_fma_f32 v[128:129], v[160:161], v[160:161], v[128:129]
	v_pk_fma_f32 v[128:129], v[162:163], v[162:163], v[128:129]
	v_pk_fma_f32 v[128:129], v[164:165], v[164:165], v[128:129]
	v_pk_fma_f32 v[128:129], v[166:167], v[166:167], v[128:129]
	v_pk_fma_f32 v[128:129], v[168:169], v[168:169], v[128:129]
	v_pk_fma_f32 v[128:129], v[170:171], v[170:171], v[128:129]
	v_add_f32_e32 v130, v128, v129
	s_nop 1
	v_add_f32_dpp v130, v130, v130 quad_perm:[1,0,3,2] row_mask:0xf bank_mask:0xf bound_ctrl:1
	s_nop 1
	v_add_f32_dpp v130, v130, v130 quad_perm:[2,3,0,1] row_mask:0xf bank_mask:0xf bound_ctrl:1
	s_nop 1
	v_add_f32_dpp v130, v130, v130 row_half_mirror row_mask:0xf bank_mask:0xf bound_ctrl:1
	s_nop 1
	v_add_f32_dpp v130, v130, v130 row_mirror row_mask:0xf bank_mask:0xf bound_ctrl:1
	s_nop 0
	v_readlane_b32 s14, v130, 0
	v_readlane_b32 s15, v130, 16
	v_readlane_b32 s6, v130, 32
	v_readlane_b32 s19, v130, 48
	s_nop 0
	v_mov_b32_e32 v128, s15
	v_add_f32_e32 v128, s14, v128
	v_mov_b32_e32 v129, s19
	v_add_f32_e32 v129, s6, v129
	v_add_f32_e32 v128, v128, v129
	v_mov_b32_e32 v129, 0x358637bd
	v_fmamk_f32 v128, v128, 0x3a000000, v129
	v_rsq_f32_e32 v128, v128
	s_nop 0
	v_readfirstlane_b32 s54, v128
	s_nop 1
	v_pk_mul_f32 v[128:129], v[140:141], s[54:55] op_sel_hi:[1,0]
	v_pk_mul_f32 v[130:131], v[142:143], s[54:55] op_sel_hi:[1,0]
	v_pk_mul_f32 v[128:129], v[0:1], v[128:129]
	v_pk_mul_f32 v[130:131], v[2:3], v[130:131]
	v_pk_fma_f32 v[128:129], v[32:33], v[128:129], v[64:65]
	v_pk_fma_f32 v[130:131], v[34:35], v[130:131], v[66:67]
	v_cvt_pk_bf16_f32 v128, v128, v129
	v_cvt_pk_bf16_f32 v129, v130, v131
	global_store_dwordx2 v132, v[128:129], s[46:47]
	v_pk_mul_f32 v[128:129], v[144:145], s[54:55] op_sel_hi:[1,0]
	v_pk_mul_f32 v[130:131], v[146:147], s[54:55] op_sel_hi:[1,0]
	v_pk_mul_f32 v[128:129], v[4:5], v[128:129]
	v_pk_mul_f32 v[130:131], v[6:7], v[130:131]
	v_pk_fma_f32 v[128:129], v[36:37], v[128:129], v[68:69]
	v_pk_fma_f32 v[130:131], v[38:39], v[130:131], v[70:71]
	v_cvt_pk_bf16_f32 v128, v128, v129
	v_cvt_pk_bf16_f32 v129, v130, v131
	global_store_dwordx2 v132, v[128:129], s[46:47] offset:512
	v_pk_mul_f32 v[128:129], v[148:149], s[54:55] op_sel_hi:[1,0]
	v_pk_mul_f32 v[130:131], v[150:151], s[54:55] op_sel_hi:[1,0]
	v_pk_mul_f32 v[128:129], v[8:9], v[128:129]
	v_pk_mul_f32 v[130:131], v[10:11], v[130:131]
	v_pk_fma_f32 v[128:129], v[40:41], v[128:129], v[72:73]
	v_pk_fma_f32 v[130:131], v[42:43], v[130:131], v[74:75]
	v_cvt_pk_bf16_f32 v128, v128, v129
	v_cvt_pk_bf16_f32 v129, v130, v131
	global_store_dwordx2 v132, v[128:129], s[46:47] offset:1024
	v_pk_mul_f32 v[128:129], v[152:153], s[54:55] op_sel_hi:[1,0]
	v_pk_mul_f32 v[130:131], v[154:155], s[54:55] op_sel_hi:[1,0]
	v_pk_mul_f32 v[128:129], v[12:13], v[128:129]
	v_pk_mul_f32 v[130:131], v[14:15], v[130:131]
	v_pk_fma_f32 v[128:129], v[44:45], v[128:129], v[76:77]
	v_pk_fma_f32 v[130:131], v[46:47], v[130:131], v[78:79]
	v_cvt_pk_bf16_f32 v128, v128, v129
	v_cvt_pk_bf16_f32 v129, v130, v131
	global_store_dwordx2 v132, v[128:129], s[46:47] offset:1536
	v_pk_mul_f32 v[128:129], v[156:157], s[54:55] op_sel_hi:[1,0]
	v_pk_mul_f32 v[130:131], v[158:159], s[54:55] op_sel_hi:[1,0]
	v_pk_mul_f32 v[128:129], v[16:17], v[128:129]
	v_pk_mul_f32 v[130:131], v[18:19], v[130:131]
	v_pk_fma_f32 v[128:129], v[48:49], v[128:129], v[80:81]
	v_pk_fma_f32 v[130:131], v[50:51], v[130:131], v[82:83]
	v_cvt_pk_bf16_f32 v128, v128, v129
	v_cvt_pk_bf16_f32 v129, v130, v131
	global_store_dwordx2 v132, v[128:129], s[46:47] offset:2048
	v_pk_mul_f32 v[128:129], v[160:161], s[54:55] op_sel_hi:[1,0]
	v_pk_mul_f32 v[130:131], v[162:163], s[54:55] op_sel_hi:[1,0]
	v_pk_mul_f32 v[128:129], v[20:21], v[128:129]
	v_pk_mul_f32 v[130:131], v[22:23], v[130:131]
	v_pk_fma_f32 v[128:129], v[52:53], v[128:129], v[84:85]
	v_pk_fma_f32 v[130:131], v[54:55], v[130:131], v[86:87]
	v_cvt_pk_bf16_f32 v128, v128, v129
	v_cvt_pk_bf16_f32 v129, v130, v131
	global_store_dwordx2 v132, v[128:129], s[46:47] offset:2560
	v_pk_mul_f32 v[128:129], v[164:165], s[54:55] op_sel_hi:[1,0]
	v_pk_mul_f32 v[130:131], v[166:167], s[54:55] op_sel_hi:[1,0]
	v_pk_mul_f32 v[128:129], v[24:25], v[128:129]
	v_pk_mul_f32 v[130:131], v[26:27], v[130:131]
	v_pk_fma_f32 v[128:129], v[56:57], v[128:129], v[88:89]
	v_pk_fma_f32 v[130:131], v[58:59], v[130:131], v[90:91]
	v_cvt_pk_bf16_f32 v128, v128, v129
	v_cvt_pk_bf16_f32 v129, v130, v131
	global_store_dwordx2 v132, v[128:129], s[46:47] offset:3072
	v_pk_mul_f32 v[128:129], v[168:169], s[54:55] op_sel_hi:[1,0]
	v_pk_mul_f32 v[130:131], v[170:171], s[54:55] op_sel_hi:[1,0]
	v_pk_mul_f32 v[128:129], v[28:29], v[128:129]
	v_pk_mul_f32 v[130:131], v[30:31], v[130:131]
	v_pk_fma_f32 v[128:129], v[60:61], v[128:129], v[92:93]
	v_pk_fma_f32 v[130:131], v[62:63], v[130:131], v[94:95]
	v_cvt_pk_bf16_f32 v128, v128, v129
	v_cvt_pk_bf16_f32 v129, v130, v131
	global_store_dwordx2 v132, v[128:129], s[46:47] offset:3584
	v_add_u32_e32 v132, 0x800000, v132
	s_add_u32 s50, s50, 0xc000
	s_addc_u32 s51, s51, 0
	s_add_u32 s52, s52, 0xc000
	s_addc_u32 s53, s53, 0
	s_add_i32 s7, s7, 1
	s_cmp_lt_u32 s7, 2
	s_cbranch_scc1 .Lnorm0_block
	s_waitcnt vmcnt(0)
	s_waitcnt vmcnt(1)
	v_mov_b32_e32 v64, v135
	s_mov_b32 s7, s78
	s_lshl_b32 s38, s7, 3
	s_add_i32 s38, s38, 0x8000
	v_ashrrev_i32_e32 v60, 6, v64
	v_add_u32_e32 v106, s38, v60
	s_mov_b32 s7, 0x8200
	v_cmp_gt_i32_e32 vcc, s7, v106
	s_mov_b32 s6, 0
	s_and_saveexec_b64 s[44:45], vcc
	s_cbranch_execz .LBB0_170
	s_load_dwordx2 s[40:41], s[0:1], s6 offset:0xe0
	s_add_u32 s46, s0, s6
	s_addc_u32 s47, s1, 0
	v_cmp_lt_i32_e32 vcc, s31, v106
	s_and_saveexec_b64 s[14:15], vcc
	s_xor_b64 s[50:51], exec, s[14:15]
	s_cbranch_execz .LBB0_140
	v_readlane_b32 s14, v255, 10
	v_readlane_b32 s15, v255, 11
	s_mov_b64 s[52:53], -1
	s_and_b64 vcc, exec, s[14:15]
	s_cbranch_vccz .LBB0_137
	s_waitcnt lgkmcnt(0)
	s_add_u32 s48, s40, 0x900000
	s_addc_u32 s49, s41, 0
	s_mov_b64 s[52:53], 0

; __device__ __forceinline__ void phase_norm(KP p, int l, int which, int nrows) {
;     ...
;   const float* mods = (const float*)(p->ws + OFF_MODS) + (size_t)l * 3 * 12288;
;   const float* g = p->in[which ? 7 : 6] + (size_t)l * DM;
;   u16* A = (u16*)(p->ws + OFF_A);
;   const int lane = tid_ & 63, wv = tid_ >> 6;
;   const int sh = which ? 3 : 0, scl = which ? 4 : 1;
;   const int stride = gridDim.x * 8;
;   float4 va[8], vb[8];
;     ...
;   int r = bid_ * 8 + wv;
;   if (r < nrows) NORM_LOAD(va, r);
.LBB0_1004:
	s_cmp_lt_i32 s6, s68
	s_cselect_b64 s[44:45], -1, 0
	s_cmp_ge_i32 s6, s68
	s_cselect_b64 s[6:7], -1, 0
	s_and_b64 s[6:7], s[40:41], s[6:7]
	s_andn2_b64 vcc, exec, s[6:7]
	s_cbranch_vccnz .LBB0_1034
	s_load_dwordx2 s[14:15], s[0:1], 0xe0
	s_load_dwordx2 s[40:41], s[0:1], 0xd8
	s_load_dwordx2 s[48:49], s[0:1], 0x38
	v_readlane_b32 s18, v255, 12
	s_waitcnt lgkmcnt(0)
	s_lshl_b32 s19, s18, 13
	s_add_u32 s48, s48, s19
	s_addc_u32 s49, s49, 0
	s_mul_i32 s19, s18, 0x24000
	s_add_u32 s50, s14, s19
	s_addc_u32 s51, s15, 0
	s_add_u32 s46, s14, 0xaa00000
	s_addc_u32 s47, s15, 0
	s_add_u32 s52, s50, 0x6000
	s_addc_u32 s53, s51, 0
	s_add_u32 s50, s50, 0x8000
	s_addc_u32 s51, s51, 0
	v_and_b32_e32 v128, 63, v135
	v_lshlrev_b32_e32 v129, 4, v128
	v_lshrrev_b32_e32 v131, 6, v135
	s_lshl_b32 s19, s78, 3
	v_add_u32_e32 v131, s19, v131
	v_lshl_add_u32 v136, v131, 13, v129
	v_add_u32_e32 v137, 0x1000, v136
	v_lshrrev_b32_e32 v132, 1, v136
	global_load_dwordx4 v[96:99], v136, s[40:41]
	global_load_dwordx4 v[100:103], v136, s[40:41] offset:1024
	global_load_dwordx4 v[104:107], v136, s[40:41] offset:2048
	global_load_dwordx4 v[108:111], v136, s[40:41] offset:3072
	global_load_dwordx4 v[112:115], v137, s[40:41]
	global_load_dwordx4 v[116:119], v137, s[40:41] offset:1024
	global_load_dwordx4 v[120:123], v137, s[40:41] offset:2048
	global_load_dwordx4 v[124:127], v137, s[40:41] offset:3072
	s_mov_b32 s7, 0

; __device__ __forceinline__ void phase_norm(KP p, int l, int which, int nrows) {
;     ...
;   int r = bid_ * 8 + wv;
;   if (r < nrows) NORM_LOAD(va, r);
;   for (; r < nrows; r += 2 * stride) {
;     if (r + stride < nrows) NORM_LOAD(vb, r + stride);
;     NORM_BODY(va, r);
;     if (r + 2 * stride < nrows) NORM_LOAD(va, r + 2 * stride);
;     if (r + stride < nrows) NORM_BODY(vb, r + stride);
;   }
.Lnorm1_nopf:
	s_waitcnt vmcnt(8)
	v_pk_mul_f32 v[128:129], v[140:141], v[140:141]
	v_pk_fma_f32 v[128:129], v[142:143], v[142:143], v[128:129]
	v_pk_fma_f32 v[128:129], v[144:145], v[144:145], v[128:129]
	v_pk_fma_f32 v[128:129], v[146:147], v[146:147], v[128:129]
	v_pk_fma_f32 v[128:129], v[148:149], v[148:149], v[128:129]
	v_pk_fma_f32 v[128:129], v[150:151], v[150:151], v[128:129]
	v_pk_fma_f32 v[128:129], v[152:153], v[152:153], v[128:129]
	v_pk_fma_f32 v[128:129], v[154:155], v[154:155], v[128:129]
	v_pk_fma_f32 v[128:129], v[156:157], v[156:157], v[128:129]
	v_pk_fma_f32 v[128:129], v[158:159], v[158:159], v[128:129]
	v_pk_fma_f32 v[128:129], v[160:161], v[160:161], v[128:129]
	v_pk_fma_f32 v[128:129], v[162:163], v[162:163], v[128:129]
	v_pk_fma_f32 v[128:129], v[164:165], v[164:165], v[128:129]
	v_pk_fma_f32 v[128:129], v[166:167], v[166:167], v[128:129]
	v_pk_fma_f32 v[128:129], v[168:169], v[168:169], v[128:129]
	v_pk_fma_f32 v[128:129], v[170:171], v[170:171], v[128:129]
	v_add_f32_e32 v130, v128, v129
	s_nop 1
	v_add_f32_dpp v130, v130, v130 quad_perm:[1,0,3,2] row_mask:0xf bank_mask:0xf bound_ctrl:1
	s_nop 1
	v_add_f32_dpp v130, v130, v130 quad_perm:[2,3,0,1] row_mask:0xf bank_mask:0xf bound_ctrl:1
	s_nop 1
	v_add_f32_dpp v130, v130, v130 row_half_mirror row_mask:0xf bank_mask:0xf bound_ctrl:1
	s_nop 1
	v_add_f32_dpp v130, v130, v130 row_mirror row_mask:0xf bank_mask:0xf bound_ctrl:1
	s_nop 0
	v_readlane_b32 s14, v130, 0
	v_readlane_b32 s15, v130, 16
	v_readlane_b32 s6, v130, 32
	v_readlane_b32 s19, v130, 48
	s_nop 0
	v_mov_b32_e32 v128, s15
	v_add_f32_e32 v128, s14, v128
	v_mov_b32_e32 v129, s19
	v_add_f32_e32 v129, s6, v129
	v_add_f32_e32 v128, v128, v129
	v_mov_b32_e32 v129, 0x358637bd
	v_fmamk_f32 v128, v128, 0x3a000000, v129
	v_rsq_f32_e32 v128, v128
	s_nop 0
	v_readfirstlane_b32 s54, v128
	s_nop 1
	v_pk_mul_f32 v[128:129], v[140:141], s[54:55] op_sel_hi:[1,0]
	v_pk_mul_f32 v[130:131], v[142:143], s[54:55] op_sel_hi:[1,0]
	v_pk_mul_f32 v[128:129], v[0:1], v[128:129]
	v_pk_mul_f32 v[130:131], v[2:3], v[130:131]
	v_pk_fma_f32 v[128:129], v[32:33], v[128:129], v[64:65]
	v_pk_fma_f32 v[130:131], v[34:35], v[130:131], v[66:67]
	v_cvt_pk_bf16_f32 v128, v128, v129
	v_cvt_pk_bf16_f32 v129, v130, v131
	global_store_dwordx2 v132, v[128:129], s[46:47]
	v_pk_mul_f32 v[128:129], v[144:145], s[54:55] op_sel_hi:[1,0]
	v_pk_mul_f32 v[130:131], v[146:147], s[54:55] op_sel_hi:[1,0]
	v_pk_mul_f32 v[128:129], v[4:5], v[128:129]
	v_pk_mul_f32 v[130:131], v[6:7], v[130:131]
	v_pk_fma_f32 v[128:129], v[36:37], v[128:129], v[68:69]
	v_pk_fma_f32 v[130:131], v[38:39], v[130:131], v[70:71]
	v_cvt_pk_bf16_f32 v128, v128, v129
	v_cvt_pk_bf16_f32 v129, v130, v131
	global_store_dwordx2 v132, v[128:129], s[46:47] offset:512
	v_pk_mul_f32 v[128:129], v[148:149], s[54:55] op_sel_hi:[1,0]
	v_pk_mul_f32 v[130:131], v[150:151], s[54:55] op_sel_hi:[1,0]
	v_pk_mul_f32 v[128:129], v[8:9], v[128:129]
	v_pk_mul_f32 v[130:131], v[10:11], v[130:131]
	v_pk_fma_f32 v[128:129], v[40:41], v[128:129], v[72:73]
	v_pk_fma_f32 v[130:131], v[42:43], v[130:131], v[74:75]
	v_cvt_pk_bf16_f32 v128, v128, v129
	v_cvt_pk_bf16_f32 v129, v130, v131
	global_store_dwordx2 v132, v[128:129], s[46:47] offset:1024
	v_pk_mul_f32 v[128:129], v[152:153], s[54:55] op_sel_hi:[1,0]
	v_pk_mul_f32 v[130:131], v[154:155], s[54:55] op_sel_hi:[1,0]
	v_pk_mul_f32 v[128:129], v[12:13], v[128:129]
	v_pk_mul_f32 v[130:131], v[14:15], v[130:131]
	v_pk_fma_f32 v[128:129], v[44:45], v[128:129], v[76:77]
	v_pk_fma_f32 v[130:131], v[46:47], v[130:131], v[78:79]
	v_cvt_pk_bf16_f32 v128, v128, v129
	v_cvt_pk_bf16_f32 v129, v130, v131
	global_store_dwordx2 v132, v[128:129], s[46:47] offset:1536
	v_pk_mul_f32 v[128:129], v[156:157], s[54:55] op_sel_hi:[1,0]
	v_pk_mul_f32 v[130:131], v[158:159], s[54:55] op_sel_hi:[1,0]
	v_pk_mul_f32 v[128:129], v[16:17], v[128:129]
	v_pk_mul_f32 v[130:131], v[18:19], v[130:131]
	v_pk_fma_f32 v[128:129], v[48:49], v[128:129], v[80:81]
	v_pk_fma_f32 v[130:131], v[50:51], v[130:131], v[82:83]
	v_cvt_pk_bf16_f32 v128, v128, v129
	v_cvt_pk_bf16_f32 v129, v130, v131
	global_store_dwordx2 v132, v[128:129], s[46:47] offset:2048
	v_pk_mul_f32 v[128:129], v[160:161], s[54:55] op_sel_hi:[1,0]
	v_pk_mul_f32 v[130:131], v[162:163], s[54:55] op_sel_hi:[1,0]
	v_pk_mul_f32 v[128:129], v[20:21], v[128:129]
	v_pk_mul_f32 v[130:131], v[22:23], v[130:131]
	v_pk_fma_f32 v[128:129], v[52:53], v[128:129], v[84:85]
	v_pk_fma_f32 v[130:131], v[54:55], v[130:131], v[86:87]
	v_cvt_pk_bf16_f32 v128, v128, v129
	v_cvt_pk_bf16_f32 v129, v130, v131
	global_store_dwordx2 v132, v[128:129], s[46:47] offset:2560
	v_pk_mul_f32 v[128:129], v[164:165], s[54:55] op_sel_hi:[1,0]
	v_pk_mul_f32 v[130:131], v[166:167], s[54:55] op_sel_hi:[1,0]
	v_pk_mul_f32 v[128:129], v[24:25], v[128:129]
	v_pk_mul_f32 v[130:131], v[26:27], v[130:131]
	v_pk_fma_f32 v[128:129], v[56:57], v[128:129], v[88:89]
	v_pk_fma_f32 v[130:131], v[58:59], v[130:131], v[90:91]
	v_cvt_pk_bf16_f32 v128, v128, v129
	v_cvt_pk_bf16_f32 v129, v130, v131
	global_store_dwordx2 v132, v[128:129], s[46:47] offset:3072
	v_pk_mul_f32 v[128:129], v[168:169], s[54:55] op_sel_hi:[1,0]
	v_pk_mul_f32 v[130:131], v[170:171], s[54:55] op_sel_hi:[1,0]
	v_pk_mul_f32 v[128:129], v[28:29], v[128:129]
	v_pk_mul_f32 v[130:131], v[30:31], v[130:131]
	v_pk_fma_f32 v[128:129], v[60:61], v[128:129], v[92:93]
	v_pk_fma_f32 v[130:131], v[62:63], v[130:131], v[94:95]
	v_cvt_pk_bf16_f32 v128, v128, v129
	v_cvt_pk_bf16_f32 v129, v130, v131
	global_store_dwordx2 v132, v[128:129], s[46:47] offset:3584
	v_add_u32_e32 v132, 0x800000, v132
	s_add_u32 s50, s50, 0xc000
	s_addc_u32 s51, s51, 0
	s_add_u32 s52, s52, 0xc000
	s_addc_u32 s53, s53, 0
	s_add_i32 s7, s7, 1
	s_cmp_lt_u32 s7, 2
	s_cbranch_scc1 .Lnorm1_block
	s_waitcnt vmcnt(0)
	v_readlane_b32 s6, v254, 57
	v_readlane_b32 s7, v254, 58
	s_and_b64 s[6:7], s[6:7], exec
	s_mov_b32 s6, 0x8000
	s_cselect_b32 s14, s6, 0x8200
	v_mov_b32_e32 v34, v135
	s_mov_b32 s6, s78
	s_lshl_b32 s40, s6, 3
	s_add_i32 s40, s40, 0x8000
	v_ashrrev_i32_e32 v32, 6, v34
	v_add_u32_e32 v76, s40, v32
	v_cmp_gt_i32_e32 vcc, s14, v76
	s_mov_b32 s15, 0
	s_and_saveexec_b64 s[46:47], vcc
	s_cbranch_execz .LBB0_1026
	s_load_dwordx2 s[42:43], s[0:1], s15 offset:0xe0
	v_cmp_lt_i32_e32 vcc, s31, v76
	s_and_saveexec_b64 s[6:7], vcc
	s_xor_b64 s[48:49], exec, s[6:7]
	s_cbranch_execz .LBB0_1008
	s_waitcnt lgkmcnt(0)
	s_add_u32 s52, s42, 0x900000
	v_add_u32_e32 v132, 0xffff8000, v76
	s_addc_u32 s53, s43, 0
	v_mov_b64_e32 v[0:1], v[132:133]
